# FF2 leftover round split-K: each of the 4 workgroups publishes f32 slabs for the rows it does not own and sums residual+own+3 slabs (fixed order) for its own quarter; per-wave hand-off
# speedup vs baseline: 1.0130x; 1.0130x over previous
; #define PG8_STAGE(bufoff, gbase, voff) do { _Pragma("unroll") for (int _i = 0; _i < 2; ++_i) \
;         __builtin_amdgcn_global_load_lds((const unsigned*)((const char*)(gbase) + (voff)[_i]), (LAS unsigned*)(lds + (bufoff) + ldsw + _i * 8192), 16, 0, 0); } while (0)
; #define PG8_LDA(dst, b, h) do { _Pragma("unroll") for (int m = 0; m < 4; ++m) _Pragma("unroll") for (int k = 0; k < 2; ++k) dst[m][k] = *(const LAS bf16x8*)(lds + PG8_SA(b, h) + aoff + m * 2048 + k * 1024); } while (0)
; #define PG8_LDB(dst, b, h) do { _Pragma("unroll") for (int n = 0; n < 2; ++n) _Pragma("unroll") for (int k = 0; k < 2; ++k) dst[n][k] = *(const LAS bf16x8*)(lds + PG8_SB(b, h) + boff + n * 2048 + k * 1024); } while (0)
; #define PG8_MMA(ai, bj, At, Bt) do { __builtin_amdgcn_s_setprio(1); _Pragma("unroll") for (int m = 0; m < 4; ++m) _Pragma("unroll") for (int n = 0; n < 2; ++n) _Pragma("unroll") for (int k = 0; k < 2; ++k) \
;         acc[ai][bj][m][n] = __builtin_amdgcn_mfma_f32_16x16x32_bf16(Bt[n][k], At[m][k], acc[ai][bj][m][n], 0, 0, 0); __builtin_amdgcn_s_setprio(0); } while (0)
; #define PG8_WAIT_V(n) asm volatile("s_waitcnt vmcnt(" #n ")" ::: "memory")
; #define PG8_WAIT_L(n) asm volatile("s_waitcnt lgkmcnt(" #n ")" ::: "memory")
; #define PG8_BAR __builtin_amdgcn_s_barrier()
; #define PG8_SCHED __builtin_amdgcn_sched_barrier(0)
; template <class Epi, class Sched>
; __device__ __forceinline__ void gemm_phase(LAS unsigned char* lds, const Gemm g, const Sched& S, const Epi& E) {
;     ...
;             PG8_LDB(B0, 0, 0); PG8_SCHED; PG8_LDA(At, 0, 0); PG8_STAGE(PG8_SA(1, 1), a1 + hstep, voffA);
;             PG8_WAIT_L(8); PG8_BAR; PG8_WAIT_L(0); PG8_MMA(0, 0, At, B0); PG8_BAR; PG8_SCHED;
;             PG8_LDB(B1, 0, 1); PG8_STAGE(PG8_SB(0, 0), b2, voffB);
;             PG8_BAR; PG8_WAIT_L(0); PG8_MMA(0, 1, At, B1); PG8_BAR;
;             PG8_LDA(At, 0, 1); PG8_STAGE(PG8_SA(0, 0), a2, voffA);
;             PG8_BAR; PG8_WAIT_L(0); PG8_MMA(1, 0, At, B0); PG8_BAR; PG8_SCHED;
;             PG8_STAGE(PG8_SB(0, 1), b2 + hstep, voffB);
;             PG8_WAIT_V(6); PG8_BAR; PG8_MMA(1, 1, At, B1); PG8_BAR;
.LBB0_1343:
	s_nop 0
	v_add_u32_e32 v136, s42, v139
	ds_read_b128 v[142:145], v136
	ds_read_b128 v[146:149], v136 offset:1024
	ds_read_b128 v[150:153], v136 offset:2048
	ds_read_b128 v[154:157], v136 offset:3072
	s_add_u32 s18, s16, 0x100
	s_addc_u32 s19, s17, 0
	s_cmpk_eq_i32 s40, 0x7c
	s_cselect_b32 s23, s3, s19
	s_cselect_b32 s22, s7, s18
	s_cselect_b32 s21, s5, s39
	s_cselect_b32 s20, s37, s38
	v_lshl_add_u64 v[136:137], s[16:17], 0, v[132:133]
	s_add_i32 m0, s13, 0xc000
	ds_read_b128 v[158:161], v141
	ds_read_b128 v[162:165], v141 offset:1024
	ds_read_b128 v[166:169], v141 offset:2048
	ds_read_b128 v[170:173], v141 offset:3072
	ds_read_b128 v[174:177], v141 offset:4096
	ds_read_b128 v[178:181], v141 offset:5120
	ds_read_b128 v[182:185], v141 offset:6144
	ds_read_b128 v[186:189], v141 offset:7168
	global_load_lds_dwordx4 v[136:137], off
	v_lshl_add_u64 v[136:137], s[16:17], 0, v[134:135]
	s_add_i32 m0, s13, 0xe000
	s_nop 0
	global_load_lds_dwordx4 v[136:137], off
	s_waitcnt lgkmcnt(8)
	s_barrier
	s_waitcnt lgkmcnt(0)
	s_setprio 1
	s_waitcnt lgkmcnt(0)
	v_mfma_f32_16x16x32_bf16 v[126:129], v[142:145], v[158:161], v[126:129]
	v_mfma_f32_16x16x32_bf16 v[122:125], v[150:153], v[158:161], v[122:125]
	v_mfma_f32_16x16x32_bf16 v[110:113], v[142:145], v[166:169], v[110:113]
	v_mfma_f32_16x16x32_bf16 v[106:109], v[150:153], v[166:169], v[106:109]
	v_mfma_f32_16x16x32_bf16 v[94:97], v[142:145], v[174:177], v[94:97]
	v_mfma_f32_16x16x32_bf16 v[90:93], v[150:153], v[174:177], v[90:93]
	v_mfma_f32_16x16x32_bf16 v[78:81], v[142:145], v[182:185], v[78:81]
	v_mfma_f32_16x16x32_bf16 v[74:77], v[150:153], v[182:185], v[74:77]
	v_mfma_f32_16x16x32_bf16 v[126:129], v[146:149], v[162:165], v[126:129]
	v_mfma_f32_16x16x32_bf16 v[122:125], v[154:157], v[162:165], v[122:125]
	v_mfma_f32_16x16x32_bf16 v[110:113], v[146:149], v[170:173], v[110:113]
	v_mfma_f32_16x16x32_bf16 v[106:109], v[154:157], v[170:173], v[106:109]
	v_mfma_f32_16x16x32_bf16 v[94:97], v[146:149], v[178:181], v[94:97]
	v_mfma_f32_16x16x32_bf16 v[90:93], v[154:157], v[178:181], v[90:93]
	v_mfma_f32_16x16x32_bf16 v[78:81], v[146:149], v[186:189], v[78:81]
	v_mfma_f32_16x16x32_bf16 v[74:77], v[154:157], v[186:189], v[74:77]
	s_setprio 0
	s_barrier
	s_add_i32 s41, 0, 0x14000
	v_add_u32_e32 v136, s41, v139
	s_add_i32 s16, s42, s28
	ds_read_b128 v[190:193], v136
	ds_read_b128 v[194:197], v136 offset:1024
	ds_read_b128 v[198:201], v136 offset:2048
	ds_read_b128 v[202:205], v136 offset:3072
	v_lshl_add_u64 v[136:137], s[20:21], 0, v[0:1]
	s_mov_b32 m0, s16
	v_lshl_add_u64 v[206:207], s[20:21], 0, v[130:131]
	global_load_lds_dwordx4 v[136:137], off
	s_add_i32 m0, s16, 0x2000
	s_nop 0
	global_load_lds_dwordx4 v[206:207], off
	s_barrier
	s_waitcnt lgkmcnt(0)
	s_setprio 1
	s_waitcnt lgkmcnt(0)
	v_mfma_f32_16x16x32_bf16 v[118:121], v[190:193], v[158:161], v[118:121]
	v_mfma_f32_16x16x32_bf16 v[114:117], v[198:201], v[158:161], v[114:117]
	v_mfma_f32_16x16x32_bf16 v[102:105], v[190:193], v[166:169], v[102:105]
	v_mfma_f32_16x16x32_bf16 v[98:101], v[198:201], v[166:169], v[98:101]
	v_mfma_f32_16x16x32_bf16 v[86:89], v[190:193], v[174:177], v[86:89]
	v_mfma_f32_16x16x32_bf16 v[82:85], v[198:201], v[174:177], v[82:85]
	v_mfma_f32_16x16x32_bf16 v[70:73], v[190:193], v[182:185], v[70:73]
	v_mfma_f32_16x16x32_bf16 v[66:69], v[198:201], v[182:185], v[66:69]
	v_mfma_f32_16x16x32_bf16 v[118:121], v[194:197], v[162:165], v[118:121]
	v_mfma_f32_16x16x32_bf16 v[114:117], v[202:205], v[162:165], v[114:117]
	v_mfma_f32_16x16x32_bf16 v[102:105], v[194:197], v[170:173], v[102:105]
	v_mfma_f32_16x16x32_bf16 v[98:101], v[202:205], v[170:173], v[98:101]
	v_mfma_f32_16x16x32_bf16 v[86:89], v[194:197], v[178:181], v[86:89]
	v_mfma_f32_16x16x32_bf16 v[82:85], v[202:205], v[178:181], v[82:85]
	v_mfma_f32_16x16x32_bf16 v[70:73], v[194:197], v[186:189], v[70:73]
	v_mfma_f32_16x16x32_bf16 v[66:69], v[202:205], v[186:189], v[66:69]
	s_setprio 0
	s_mov_b32 m0, s13
	v_lshl_add_u64 v[208:209], s[22:23], 0, v[0:1]
	s_barrier
	ds_read_b128 v[158:161], v141 offset:16384
	ds_read_b128 v[162:165], v141 offset:17408
	ds_read_b128 v[166:169], v141 offset:18432
	ds_read_b128 v[170:173], v141 offset:19456
	ds_read_b128 v[174:177], v141 offset:20480
	ds_read_b128 v[178:181], v141 offset:21504
	ds_read_b128 v[182:185], v141 offset:22528
	ds_read_b128 v[186:189], v141 offset:23552
	global_load_lds_dwordx4 v[208:209], off
	v_lshl_add_u64 v[210:211], s[22:23], 0, v[130:131]
	s_mov_b32 m0, s15
	s_nop 0
	global_load_lds_dwordx4 v[210:211], off
	s_barrier
	s_waitcnt lgkmcnt(0)
	s_setprio 1
	s_waitcnt lgkmcnt(0)
	v_mfma_f32_16x16x32_bf16 v[62:65], v[142:145], v[158:161], v[62:65]
	v_mfma_f32_16x16x32_bf16 v[58:61], v[150:153], v[158:161], v[58:61]
	v_mfma_f32_16x16x32_bf16 v[46:49], v[142:145], v[166:169], v[46:49]
	v_mfma_f32_16x16x32_bf16 v[42:45], v[150:153], v[166:169], v[42:45]
	v_mfma_f32_16x16x32_bf16 v[30:33], v[142:145], v[174:177], v[30:33]
	v_mfma_f32_16x16x32_bf16 v[26:29], v[150:153], v[174:177], v[26:29]
	v_mfma_f32_16x16x32_bf16 v[14:17], v[142:145], v[182:185], v[14:17]
	v_mfma_f32_16x16x32_bf16 v[10:13], v[150:153], v[182:185], v[10:13]
	v_mfma_f32_16x16x32_bf16 v[62:65], v[146:149], v[162:165], v[62:65]
	v_mfma_f32_16x16x32_bf16 v[58:61], v[154:157], v[162:165], v[58:61]
	v_mfma_f32_16x16x32_bf16 v[46:49], v[146:149], v[170:173], v[46:49]
	v_mfma_f32_16x16x32_bf16 v[42:45], v[154:157], v[170:173], v[42:45]
	v_mfma_f32_16x16x32_bf16 v[30:33], v[146:149], v[178:181], v[30:33]
	v_mfma_f32_16x16x32_bf16 v[26:29], v[154:157], v[178:181], v[26:29]
	v_mfma_f32_16x16x32_bf16 v[14:17], v[146:149], v[186:189], v[14:17]
	v_mfma_f32_16x16x32_bf16 v[10:13], v[154:157], v[186:189], v[10:13]
	s_setprio 0
	s_barrier
; #define PG8_STAGE(bufoff, gbase, voff) do { _Pragma("unroll") for (int _i = 0; _i < 2; ++_i) \
;         __builtin_amdgcn_global_load_lds((const unsigned*)((const char*)(gbase) + (voff)[_i]), (LAS unsigned*)(lds + (bufoff) + ldsw + _i * 8192), 16, 0, 0); } while (0)
; #define PG8_LDA(dst, b, h) do { _Pragma("unroll") for (int m = 0; m < 4; ++m) _Pragma("unroll") for (int k = 0; k < 2; ++k) dst[m][k] = *(const LAS bf16x8*)(lds + PG8_SA(b, h) + aoff + m * 2048 + k * 1024); } while (0)
; #define PG8_LDB(dst, b, h) do { _Pragma("unroll") for (int n = 0; n < 2; ++n) _Pragma("unroll") for (int k = 0; k < 2; ++k) dst[n][k] = *(const LAS bf16x8*)(lds + PG8_SB(b, h) + boff + n * 2048 + k * 1024); } while (0)
; #define PG8_MMA(ai, bj, At, Bt) do { __builtin_amdgcn_s_setprio(1); _Pragma("unroll") for (int m = 0; m < 4; ++m) _Pragma("unroll") for (int n = 0; n < 2; ++n) _Pragma("unroll") for (int k = 0; k < 2; ++k) \
;         acc[ai][bj][m][n] = __builtin_amdgcn_mfma_f32_16x16x32_bf16(Bt[n][k], At[m][k], acc[ai][bj][m][n], 0, 0, 0); __builtin_amdgcn_s_setprio(0); } while (0)
; #define PG8_WAIT_V(n) asm volatile("s_waitcnt vmcnt(" #n ")" ::: "memory")
; #define PG8_WAIT_L(n) asm volatile("s_waitcnt lgkmcnt(" #n ")" ::: "memory")
; #define PG8_BAR __builtin_amdgcn_s_barrier()
; #define PG8_SCHED __builtin_amdgcn_sched_barrier(0)
; template <class Epi, class Sched>
; __device__ __forceinline__ void gemm_phase(LAS unsigned char* lds, const Gemm g, const Sched& S, const Epi& E) {
;     ...
;             PG8_BAR; PG8_WAIT_L(0); PG8_MMA(1, 0, At, B0); PG8_BAR; PG8_SCHED;
;             PG8_STAGE(PG8_SB(0, 1), b2 + hstep, voffB);
;             PG8_WAIT_V(6); PG8_BAR; PG8_MMA(1, 1, At, B1); PG8_BAR;
;             PG8_LDB(B0, 1, 0); PG8_SCHED; PG8_LDA(At, 1, 0); PG8_STAGE(PG8_SA(0, 1), a2 + hstep, voffA);
;             PG8_WAIT_L(8); PG8_BAR; PG8_WAIT_L(0); PG8_MMA(0, 0, At, B0); PG8_BAR; PG8_SCHED;
;             PG8_LDB(B1, 1, 1); PG8_STAGE(PG8_SB(1, 0), b3, voffB);
;             PG8_BAR; PG8_WAIT_L(0); PG8_MMA(0, 1, At, B1); PG8_BAR;
	s_add_u32 s16, s20, 0x200000
	s_addc_u32 s17, s21, 0
	s_add_i32 s41, s41, s28
	v_lshl_add_u64 v[142:143], s[16:17], 0, v[0:1]
	s_mov_b32 m0, s41
	s_nop 0
	global_load_lds_dwordx4 v[142:143], off
	v_lshl_add_u64 v[142:143], s[16:17], 0, v[130:131]
	s_add_i32 m0, s41, 0x2000
	s_nop 0
	global_load_lds_dwordx4 v[142:143], off
	s_waitcnt vmcnt(6)
	s_barrier
	s_setprio 1
	v_mfma_f32_16x16x32_bf16 v[54:57], v[190:193], v[158:161], v[54:57]
	v_mfma_f32_16x16x32_bf16 v[50:53], v[198:201], v[158:161], v[50:53]
	v_mfma_f32_16x16x32_bf16 v[38:41], v[190:193], v[166:169], v[38:41]
	v_mfma_f32_16x16x32_bf16 v[34:37], v[198:201], v[166:169], v[34:37]
	v_mfma_f32_16x16x32_bf16 v[22:25], v[190:193], v[174:177], v[22:25]
	v_mfma_f32_16x16x32_bf16 v[18:21], v[198:201], v[174:177], v[18:21]
	v_mfma_f32_16x16x32_bf16 v[6:9], v[190:193], v[182:185], v[6:9]
	v_mfma_f32_16x16x32_bf16 v[2:5], v[198:201], v[182:185], v[2:5]
	v_mfma_f32_16x16x32_bf16 v[54:57], v[194:197], v[162:165], v[54:57]
	v_mfma_f32_16x16x32_bf16 v[50:53], v[202:205], v[162:165], v[50:53]
	v_mfma_f32_16x16x32_bf16 v[38:41], v[194:197], v[170:173], v[38:41]
	v_mfma_f32_16x16x32_bf16 v[34:37], v[202:205], v[170:173], v[34:37]
	v_mfma_f32_16x16x32_bf16 v[22:25], v[194:197], v[178:181], v[22:25]
	v_mfma_f32_16x16x32_bf16 v[18:21], v[202:205], v[178:181], v[18:21]
	v_mfma_f32_16x16x32_bf16 v[6:9], v[194:197], v[186:189], v[6:9]
	v_mfma_f32_16x16x32_bf16 v[2:5], v[202:205], v[186:189], v[2:5]
	s_setprio 0
	s_add_i32 s41, 0, 0x18000
	v_add_u32_e32 v154, s41, v139
	s_barrier
	ds_read_b128 v[142:145], v154
	ds_read_b128 v[146:149], v154 offset:1024
	ds_read_b128 v[150:153], v154 offset:2048
	ds_read_b128 v[154:157], v154 offset:3072
	s_add_u32 s16, s22, 0x200000
	s_addc_u32 s17, s23, 0
	s_mov_b32 m0, s29
	v_lshl_add_u64 v[190:191], s[16:17], 0, v[0:1]
	ds_read_b128 v[158:161], v141 offset:32768
	ds_read_b128 v[162:165], v141 offset:33792
	ds_read_b128 v[166:169], v141 offset:34816
	ds_read_b128 v[170:173], v141 offset:35840
	ds_read_b128 v[174:177], v141 offset:36864
	ds_read_b128 v[178:181], v141 offset:37888
	ds_read_b128 v[182:185], v141 offset:38912
	ds_read_b128 v[186:189], v141 offset:39936
	global_load_lds_dwordx4 v[190:191], off
	v_lshl_add_u64 v[190:191], s[16:17], 0, v[130:131]
	s_mov_b32 m0, s30
	s_nop 0
	global_load_lds_dwordx4 v[190:191], off
	s_waitcnt lgkmcnt(8)
	s_barrier
	s_waitcnt lgkmcnt(0)
	s_setprio 1
	s_waitcnt lgkmcnt(0)
	v_mfma_f32_16x16x32_bf16 v[126:129], v[142:145], v[158:161], v[126:129]
	v_mfma_f32_16x16x32_bf16 v[122:125], v[150:153], v[158:161], v[122:125]
	v_mfma_f32_16x16x32_bf16 v[110:113], v[142:145], v[166:169], v[110:113]
	v_mfma_f32_16x16x32_bf16 v[106:109], v[150:153], v[166:169], v[106:109]
	v_mfma_f32_16x16x32_bf16 v[94:97], v[142:145], v[174:177], v[94:97]
	v_mfma_f32_16x16x32_bf16 v[90:93], v[150:153], v[174:177], v[90:93]
	v_mfma_f32_16x16x32_bf16 v[78:81], v[142:145], v[182:185], v[78:81]
	v_mfma_f32_16x16x32_bf16 v[74:77], v[150:153], v[182:185], v[74:77]
	v_mfma_f32_16x16x32_bf16 v[126:129], v[146:149], v[162:165], v[126:129]
	v_mfma_f32_16x16x32_bf16 v[122:125], v[154:157], v[162:165], v[122:125]
	v_mfma_f32_16x16x32_bf16 v[110:113], v[146:149], v[170:173], v[110:113]
	v_mfma_f32_16x16x32_bf16 v[106:109], v[154:157], v[170:173], v[106:109]
	v_mfma_f32_16x16x32_bf16 v[94:97], v[146:149], v[178:181], v[94:97]
	v_mfma_f32_16x16x32_bf16 v[90:93], v[154:157], v[178:181], v[90:93]
	v_mfma_f32_16x16x32_bf16 v[78:81], v[146:149], v[186:189], v[78:81]
	v_mfma_f32_16x16x32_bf16 v[74:77], v[154:157], v[186:189], v[74:77]
	s_setprio 0
	s_barrier
	s_add_i32 s22, 0, 0x1c000
	s_add_i32 s16, s41, s28
	v_add_u32_e32 v202, s22, v139
	v_lshl_add_u64 v[136:137], v[136:137], 0, s[44:45]
	s_mov_b32 m0, s16
	ds_read_b128 v[190:193], v202
	ds_read_b128 v[194:197], v202 offset:1024
	ds_read_b128 v[198:201], v202 offset:2048
	ds_read_b128 v[202:205], v202 offset:3072
	global_load_lds_dwordx4 v[136:137], off
	v_lshl_add_u64 v[136:137], v[206:207], 0, s[44:45]
	s_add_i32 m0, s16, 0x2000
	s_nop 0
	global_load_lds_dwordx4 v[136:137], off
	s_barrier
	s_waitcnt lgkmcnt(0)
	s_setprio 1
	s_waitcnt lgkmcnt(0)
	v_mfma_f32_16x16x32_bf16 v[118:121], v[190:193], v[158:161], v[118:121]
	v_mfma_f32_16x16x32_bf16 v[114:117], v[198:201], v[158:161], v[114:117]
	v_mfma_f32_16x16x32_bf16 v[102:105], v[190:193], v[166:169], v[102:105]
	v_mfma_f32_16x16x32_bf16 v[98:101], v[198:201], v[166:169], v[98:101]
	v_mfma_f32_16x16x32_bf16 v[86:89], v[190:193], v[174:177], v[86:89]
	v_mfma_f32_16x16x32_bf16 v[82:85], v[198:201], v[174:177], v[82:85]
	v_mfma_f32_16x16x32_bf16 v[70:73], v[190:193], v[182:185], v[70:73]
	v_mfma_f32_16x16x32_bf16 v[66:69], v[198:201], v[182:185], v[66:69]
	v_mfma_f32_16x16x32_bf16 v[118:121], v[194:197], v[162:165], v[118:121]
	v_mfma_f32_16x16x32_bf16 v[114:117], v[202:205], v[162:165], v[114:117]
	v_mfma_f32_16x16x32_bf16 v[102:105], v[194:197], v[170:173], v[102:105]
	v_mfma_f32_16x16x32_bf16 v[98:101], v[202:205], v[170:173], v[98:101]
	v_mfma_f32_16x16x32_bf16 v[86:89], v[194:197], v[178:181], v[86:89]
	v_mfma_f32_16x16x32_bf16 v[82:85], v[202:205], v[178:181], v[82:85]
	v_mfma_f32_16x16x32_bf16 v[70:73], v[194:197], v[186:189], v[70:73]
	v_mfma_f32_16x16x32_bf16 v[66:69], v[202:205], v[186:189], v[66:69]
	s_setprio 0
	s_mov_b32 m0, s34
	v_lshl_add_u64 v[136:137], v[208:209], 0, s[44:45]
	s_barrier
	ds_read_b128 v[158:161], v141 offset:49152
	ds_read_b128 v[162:165], v141 offset:50176
	ds_read_b128 v[166:169], v141 offset:51200
	ds_read_b128 v[170:173], v141 offset:52224
	ds_read_b128 v[174:177], v141 offset:53248
	ds_read_b128 v[178:181], v141 offset:54272
	ds_read_b128 v[182:185], v141 offset:55296
	ds_read_b128 v[186:189], v141 offset:56320
	global_load_lds_dwordx4 v[136:137], off
	v_lshl_add_u64 v[136:137], v[210:211], 0, s[44:45]
	s_mov_b32 m0, s35
	s_nop 0
	global_load_lds_dwordx4 v[136:137], off
	s_barrier
; #define PG8_STAGE(bufoff, gbase, voff) do { _Pragma("unroll") for (int _i = 0; _i < 2; ++_i) \
;         __builtin_amdgcn_global_load_lds((const unsigned*)((const char*)(gbase) + (voff)[_i]), (LAS unsigned*)(lds + (bufoff) + ldsw + _i * 8192), 16, 0, 0); } while (0)
; #define PG8_LDA(dst, b, h) do { _Pragma("unroll") for (int m = 0; m < 4; ++m) _Pragma("unroll") for (int k = 0; k < 2; ++k) dst[m][k] = *(const LAS bf16x8*)(lds + PG8_SA(b, h) + aoff + m * 2048 + k * 1024); } while (0)
; #define PG8_MMA(ai, bj, At, Bt) do { __builtin_amdgcn_s_setprio(1); _Pragma("unroll") for (int m = 0; m < 4; ++m) _Pragma("unroll") for (int n = 0; n < 2; ++n) _Pragma("unroll") for (int k = 0; k < 2; ++k) \
;         acc[ai][bj][m][n] = __builtin_amdgcn_mfma_f32_16x16x32_bf16(Bt[n][k], At[m][k], acc[ai][bj][m][n], 0, 0, 0); __builtin_amdgcn_s_setprio(0); } while (0)
; #define PG8_WAIT_V(n) asm volatile("s_waitcnt vmcnt(" #n ")" ::: "memory")
; #define PG8_WAIT_L(n) asm volatile("s_waitcnt lgkmcnt(" #n ")" ::: "memory")
; #define PG8_BAR __builtin_amdgcn_s_barrier()
; #define PG8_SCHED __builtin_amdgcn_sched_barrier(0)
; template <class Epi, class Sched>
; __device__ __forceinline__ void gemm_phase(LAS unsigned char* lds, const Gemm g, const Sched& S, const Epi& E) {
;     ...
;             PG8_BAR; PG8_WAIT_L(0); PG8_MMA(0, 1, At, B1); PG8_BAR;
;             PG8_LDA(At, 1, 1); PG8_STAGE(PG8_SA(1, 0), a3, voffA);
;             PG8_BAR; PG8_WAIT_L(0); PG8_MMA(1, 0, At, B0); PG8_BAR; PG8_SCHED;
;             PG8_STAGE(PG8_SB(1, 1), b3 + hstep, voffB);
;             PG8_WAIT_V(6); PG8_BAR; PG8_MMA(1, 1, At, B1); PG8_BAR;
;     __device__ __forceinline__ void operator()(const f32x4 (&acc)[2][2][4][2], const pg8::Unit& u, int wr, int wc, int fr, int fq) const {
;         const int row0 = u.pm * 256 + wr * 64 + fr; const int col0 = u.pn * 256 + wc * 32 + 4 * fq;
; #pragma unroll
;         for (int ai = 0; ai < 2; ++ai)
; #pragma unroll
;             for (int m = 0; m < 4; ++m) { const int row = row0 + ai * 128 + m * 16;
;                 const float* ip; float* op; int b;
;                 if (row < ML_ROWS) { b = row >> 11; ip = xi + (size_t)row * D; op = xo + (size_t)row * D; }
;                 else { b = 8; ip = ci + (size_t)(row - ML_ROWS) * D; op = co + (size_t)(row - ML_ROWS) * D; }
;                 const float* gp = mod + (size_t)b * 12288 + slot * 2048;
	s_waitcnt lgkmcnt(0)
	s_setprio 1
	s_waitcnt lgkmcnt(0)
	v_mfma_f32_16x16x32_bf16 v[62:65], v[142:145], v[158:161], v[62:65]
	v_mfma_f32_16x16x32_bf16 v[58:61], v[150:153], v[158:161], v[58:61]
	v_mfma_f32_16x16x32_bf16 v[46:49], v[142:145], v[166:169], v[46:49]
	v_mfma_f32_16x16x32_bf16 v[42:45], v[150:153], v[166:169], v[42:45]
	v_mfma_f32_16x16x32_bf16 v[30:33], v[142:145], v[174:177], v[30:33]
	v_mfma_f32_16x16x32_bf16 v[26:29], v[150:153], v[174:177], v[26:29]
	v_mfma_f32_16x16x32_bf16 v[14:17], v[142:145], v[182:185], v[14:17]
	v_mfma_f32_16x16x32_bf16 v[10:13], v[150:153], v[182:185], v[10:13]
	v_mfma_f32_16x16x32_bf16 v[62:65], v[146:149], v[162:165], v[62:65]
	v_mfma_f32_16x16x32_bf16 v[58:61], v[154:157], v[162:165], v[58:61]
	v_mfma_f32_16x16x32_bf16 v[46:49], v[146:149], v[170:173], v[46:49]
	v_mfma_f32_16x16x32_bf16 v[42:45], v[154:157], v[170:173], v[42:45]
	v_mfma_f32_16x16x32_bf16 v[30:33], v[146:149], v[178:181], v[30:33]
	v_mfma_f32_16x16x32_bf16 v[26:29], v[154:157], v[178:181], v[26:29]
	v_mfma_f32_16x16x32_bf16 v[14:17], v[146:149], v[186:189], v[14:17]
	v_mfma_f32_16x16x32_bf16 v[10:13], v[154:157], v[186:189], v[10:13]
	s_setprio 0
	s_barrier
	s_add_u32 s16, s20, 0x200080
	s_addc_u32 s17, s21, 0
	s_add_i32 s20, s22, s28
	v_lshl_add_u64 v[136:137], s[16:17], 0, v[0:1]
	s_mov_b32 m0, s20
	s_nop 0
	global_load_lds_dwordx4 v[136:137], off
	v_lshl_add_u64 v[136:137], s[16:17], 0, v[130:131]
	s_add_i32 m0, s20, 0x2000
	s_nop 0
	global_load_lds_dwordx4 v[136:137], off
	s_waitcnt vmcnt(6)
	s_barrier
	s_setprio 1
	v_mfma_f32_16x16x32_bf16 v[54:57], v[190:193], v[158:161], v[54:57]
	v_mfma_f32_16x16x32_bf16 v[50:53], v[198:201], v[158:161], v[50:53]
	v_mfma_f32_16x16x32_bf16 v[38:41], v[190:193], v[166:169], v[38:41]
	v_mfma_f32_16x16x32_bf16 v[34:37], v[198:201], v[166:169], v[34:37]
	v_mfma_f32_16x16x32_bf16 v[22:25], v[190:193], v[174:177], v[22:25]
	v_mfma_f32_16x16x32_bf16 v[18:21], v[198:201], v[174:177], v[18:21]
	v_mfma_f32_16x16x32_bf16 v[6:9], v[190:193], v[182:185], v[6:9]
	v_mfma_f32_16x16x32_bf16 v[2:5], v[198:201], v[182:185], v[2:5]
	v_mfma_f32_16x16x32_bf16 v[54:57], v[194:197], v[162:165], v[54:57]
	v_mfma_f32_16x16x32_bf16 v[50:53], v[202:205], v[162:165], v[50:53]
	v_mfma_f32_16x16x32_bf16 v[38:41], v[194:197], v[170:173], v[38:41]
	v_mfma_f32_16x16x32_bf16 v[34:37], v[202:205], v[170:173], v[34:37]
	v_mfma_f32_16x16x32_bf16 v[22:25], v[194:197], v[178:181], v[22:25]
	v_mfma_f32_16x16x32_bf16 v[18:21], v[202:205], v[178:181], v[18:21]
	v_mfma_f32_16x16x32_bf16 v[6:9], v[194:197], v[186:189], v[6:9]
	v_mfma_f32_16x16x32_bf16 v[2:5], v[202:205], v[186:189], v[2:5]
	s_setprio 0
	s_add_i32 s40, s40, 2
	s_add_u32 s38, s38, 0x100
	s_addc_u32 s39, s39, 0
	s_cmpk_gt_u32 s40, 0x7d
	s_mov_b64 s[16:17], s[18:19]
	s_barrier
	s_cbranch_scc0 .LBB0_1343
	s_lshl_b32 s3, s14, 8
	s_add_i32 s3, s3, s31
	v_readlane_b32 s40, v251, 0
	v_readlane_b32 s41, v251, 1
	v_readlane_b32 s42, v251, 2
	v_readlane_b32 s43, v251, 3
	v_readlane_b32 s44, v251, 4
	v_readlane_b32 s45, v251, 5
	v_readlane_b32 s46, v251, 6
	v_readlane_b32 s47, v251, 7
	v_readlane_b32 s18, v254, 2
	v_readlane_b32 s19, v254, 3
	s_add_i32 s5, s3, 0xffffc000
	s_ashr_i32 s7, s3, 11
	s_cmpk_lt_i32 s3, 0x4000
	s_cselect_b32 s20, s42, s60
	s_cselect_b32 s21, s43, s61
	s_cselect_b32 s5, s3, s5
	s_cselect_b32 s7, s7, 8
	s_mul_i32 s7, s7, 0xc000
	s_add_u32 s18, s18, s7
	s_addc_u32 s19, s19, 0
	s_add_u32 s18, s18, 0xa000
	s_addc_u32 s19, s19, 0
	v_add_u32_e32 v136, s5, v138
	v_lshl_or_b32 v137, s12, 8, v140
	v_lshlrev_b32_e32 v137, 2, v137
	v_lshl_or_b32 v136, v136, 13, v137
	s_mov_b32 s12, s4
	s_mov_b32 s14, s6
	s_cmp_lg_u32 s36, 3
	s_cbranch_scc1 .Lsk_normal
	v_readlane_b32 s5, v253, 24
	s_cmpk_lg_u32 s46, 0x100
	s_cbranch_scc1 .Lsk_normal
	s_cmpk_lg_u32 s5, 0x240
	s_cbranch_scc1 .Lsk_normal
	s_and_b32 s7, s54, 3
	s_lshr_b32 s5, s54, 2
	s_lshr_b32 s3, s24, 6
	s_lshl_b32 s23, s5, 3
	s_add_i32 s23, s23, s3
	s_lshl_b32 s23, s23, 2
	v_readlane_b32 s38, v251, 10
	v_readlane_b32 s39, v251, 11
	s_add_u32 s38, s38, s23
	s_addc_u32 s39, s39, 0
	s_add_u32 s38, s38, 0x3700
	s_addc_u32 s39, s39, 0
	v_readlane_b32 s16, v251, 4
	v_readlane_b32 s17, v251, 5
	s_lshl_b32 s5, s5, 20
	s_add_u32 s16, s16, 0x24000000
	s_addc_u32 s17, s17, 0
	s_add_u32 s16, s16, s5
	s_addc_u32 s17, s17, 0
	v_add_u32_e32 v142, s31, v138
	v_lshlrev_b32_e32 v143, 2, v140
	v_lshl_or_b32 v142, v142, 10, v143
	global_load_dwordx4 v[146:149], v137, s[18:19]
	global_load_dwordx4 v[150:153], v137, s[18:19] offset:64
	global_load_dwordx4 v[154:157], v137, s[18:19] offset:512
	global_load_dwordx4 v[158:161], v137, s[18:19] offset:576
	s_cmp_eq_u32 s7, 1
	s_cbranch_scc1 .Lsk_v1
	s_cmp_eq_u32 s7, 2
	s_cbranch_scc1 .Lsk_v2
	s_cmp_eq_u32 s7, 3
	s_cbranch_scc1 .Lsk_v3
;     __device__ __forceinline__ void operator()(const f32x4 (&acc)[2][2][4][2], const pg8::Unit& u, int wr, int wc, int fr, int fq) const {
;     ...
;                 for (int bj = 0; bj < 2; ++bj)
; #pragma unroll
;                     for (int n = 0; n < 2; ++n) { const int c = col0 + bj * 128 + n * 16;
;                         const f32x4 r = *(const f32x4*)(ip + c), g = *(const f32x4*)(gp + c);
;                         *(f32x4*)(op + c) = r + g * acc[ai][bj][m][n]; } }
.Lsk_v0:
	s_waitcnt vmcnt(0)
	s_add_u32 s22, s16, 0x0
	s_addc_u32 s23, s17, 0
	v_add_u32_e32 v143, 0x8000, v142
	v_pk_mul_f32 v[94:95], v[94:95], v[146:147]
	v_pk_mul_f32 v[96:97], v[96:97], v[148:149]
	v_pk_mul_f32 v[90:91], v[90:91], v[150:151]
	v_pk_mul_f32 v[92:93], v[92:93], v[152:153]
	v_pk_mul_f32 v[86:87], v[86:87], v[154:155]
	v_pk_mul_f32 v[88:89], v[88:89], v[156:157]
	v_pk_mul_f32 v[82:83], v[82:83], v[158:159]
	v_pk_mul_f32 v[84:85], v[84:85], v[160:161]
	global_store_dwordx4 v143, v[94:97], s[22:23] sc0 sc1
	global_store_dwordx4 v143, v[90:93], s[22:23] offset:64 sc0 sc1
	global_store_dwordx4 v143, v[86:89], s[22:23] offset:512 sc0 sc1
	global_store_dwordx4 v143, v[82:85], s[22:23] offset:576 sc0 sc1
	v_add_u32_e32 v143, 0xc000, v142
	v_pk_mul_f32 v[78:79], v[78:79], v[146:147]
	v_pk_mul_f32 v[80:81], v[80:81], v[148:149]
	v_pk_mul_f32 v[74:75], v[74:75], v[150:151]
	v_pk_mul_f32 v[76:77], v[76:77], v[152:153]
	v_pk_mul_f32 v[70:71], v[70:71], v[154:155]
	v_pk_mul_f32 v[72:73], v[72:73], v[156:157]
	v_pk_mul_f32 v[66:67], v[66:67], v[158:159]
	v_pk_mul_f32 v[68:69], v[68:69], v[160:161]
	global_store_dwordx4 v143, v[78:81], s[22:23] sc0 sc1
	global_store_dwordx4 v143, v[74:77], s[22:23] offset:64 sc0 sc1
	global_store_dwordx4 v143, v[70:73], s[22:23] offset:512 sc0 sc1
	global_store_dwordx4 v143, v[66:69], s[22:23] offset:576 sc0 sc1
	v_add_u32_e32 v143, 0x20000, v142
	v_pk_mul_f32 v[62:63], v[62:63], v[146:147]
	v_pk_mul_f32 v[64:65], v[64:65], v[148:149]
	v_pk_mul_f32 v[58:59], v[58:59], v[150:151]
	v_pk_mul_f32 v[60:61], v[60:61], v[152:153]
	v_pk_mul_f32 v[54:55], v[54:55], v[154:155]
	v_pk_mul_f32 v[56:57], v[56:57], v[156:157]
	v_pk_mul_f32 v[50:51], v[50:51], v[158:159]
	v_pk_mul_f32 v[52:53], v[52:53], v[160:161]
	global_store_dwordx4 v143, v[62:65], s[22:23] sc0 sc1
	global_store_dwordx4 v143, v[58:61], s[22:23] offset:64 sc0 sc1
	global_store_dwordx4 v143, v[54:57], s[22:23] offset:512 sc0 sc1
	global_store_dwordx4 v143, v[50:53], s[22:23] offset:576 sc0 sc1
	v_add_u32_e32 v143, 0x24000, v142
	v_pk_mul_f32 v[46:47], v[46:47], v[146:147]
	v_pk_mul_f32 v[48:49], v[48:49], v[148:149]
	v_pk_mul_f32 v[42:43], v[42:43], v[150:151]
	v_pk_mul_f32 v[44:45], v[44:45], v[152:153]
	v_pk_mul_f32 v[38:39], v[38:39], v[154:155]
	v_pk_mul_f32 v[40:41], v[40:41], v[156:157]
	v_pk_mul_f32 v[34:35], v[34:35], v[158:159]
	v_pk_mul_f32 v[36:37], v[36:37], v[160:161]
	global_store_dwordx4 v143, v[46:49], s[22:23] sc0 sc1
	global_store_dwordx4 v143, v[42:45], s[22:23] offset:64 sc0 sc1
	global_store_dwordx4 v143, v[38:41], s[22:23] offset:512 sc0 sc1
	global_store_dwordx4 v143, v[34:37], s[22:23] offset:576 sc0 sc1
	v_add_u32_e32 v143, 0x28000, v142
	v_pk_mul_f32 v[30:31], v[30:31], v[146:147]
	v_pk_mul_f32 v[32:33], v[32:33], v[148:149]
	v_pk_mul_f32 v[26:27], v[26:27], v[150:151]
	v_pk_mul_f32 v[28:29], v[28:29], v[152:153]
	v_pk_mul_f32 v[22:23], v[22:23], v[154:155]
	v_pk_mul_f32 v[24:25], v[24:25], v[156:157]
	v_pk_mul_f32 v[18:19], v[18:19], v[158:159]
	v_pk_mul_f32 v[20:21], v[20:21], v[160:161]
	global_store_dwordx4 v143, v[30:33], s[22:23] sc0 sc1
	global_store_dwordx4 v143, v[26:29], s[22:23] offset:64 sc0 sc1
	global_store_dwordx4 v143, v[22:25], s[22:23] offset:512 sc0 sc1
	global_store_dwordx4 v143, v[18:21], s[22:23] offset:576 sc0 sc1
	v_add_u32_e32 v143, 0x2c000, v142
	v_pk_mul_f32 v[14:15], v[14:15], v[146:147]
	v_pk_mul_f32 v[16:17], v[16:17], v[148:149]
	v_pk_mul_f32 v[10:11], v[10:11], v[150:151]
	v_pk_mul_f32 v[12:13], v[12:13], v[152:153]
	v_pk_mul_f32 v[6:7], v[6:7], v[154:155]
	v_pk_mul_f32 v[8:9], v[8:9], v[156:157]
	v_pk_mul_f32 v[2:3], v[2:3], v[158:159]
	v_pk_mul_f32 v[4:5], v[4:5], v[160:161]
	global_store_dwordx4 v143, v[14:17], s[22:23] sc0 sc1
	global_store_dwordx4 v143, v[10:13], s[22:23] offset:64 sc0 sc1
	global_store_dwordx4 v143, v[6:9], s[22:23] offset:512 sc0 sc1
	global_store_dwordx4 v143, v[2:5], s[22:23] offset:576 sc0 sc1
	s_waitcnt vmcnt(0)
	s_mov_b64 s[22:23], exec
	s_mov_b64 exec, 1
	v_mov_b32_e32 v143, 0
	v_mov_b32_e32 v144, 1
	global_atomic_add v143, v144, s[38:39]
	s_mov_b64 exec, s[22:23]
	v_mov_b32_e32 v143, 0
	s_mov_b32 s3, 0
.Lsk_spin0:
	global_load_dword v144, v143, s[38:39] sc1
	s_waitcnt vmcnt(0)
	v_readfirstlane_b32 s5, v144
	s_cmp_ge_u32 s5, 4
	s_cbranch_scc1 .Lsk_spun0
	s_add_i32 s3, s3, 1
	s_cmp_gt_u32 s3, 0x8000
	s_cbranch_scc1 .Lsk_spun0
	s_sleep 1
	s_branch .Lsk_spin0
;     __device__ __forceinline__ void operator()(const f32x4 (&acc)[2][2][4][2], const pg8::Unit& u, int wr, int wc, int fr, int fq) const {
;     ...
;                     for (int n = 0; n < 2; ++n) { const int c = col0 + bj * 128 + n * 16;
;                         const f32x4 r = *(const f32x4*)(ip + c), g = *(const f32x4*)(gp + c);
;                         *(f32x4*)(op + c) = r + g * acc[ai][bj][m][n]; } }
.Lsk_spun0:
	buffer_inv sc1
	s_waitcnt vmcnt(0)
	s_add_u32 s22, s16, 0x40000
	s_addc_u32 s23, s17, 0
	s_add_u32 s38, s16, 0x80000
	s_addc_u32 s39, s17, 0
	s_add_u32 s16, s16, 0xc0000
	s_addc_u32 s17, s17, 0
	v_add_u32_e32 v144, 0x0, v136
	v_add_u32_e32 v210, 0x0, v142
	v_add_u32_e32 v145, 0x20000, v136
	v_add_u32_e32 v211, 0x4000, v142
	global_load_dwordx4 v[162:165], v144, s[20:21]
	global_load_dwordx4 v[166:169], v210, s[22:23]
	global_load_dwordx4 v[170:173], v210, s[38:39]
	global_load_dwordx4 v[174:177], v210, s[16:17]
	global_load_dwordx4 v[178:181], v144, s[20:21] offset:64
	global_load_dwordx4 v[182:185], v210, s[22:23] offset:64
	global_load_dwordx4 v[186:189], v210, s[38:39] offset:64
	global_load_dwordx4 v[190:193], v210, s[16:17] offset:64
	global_load_dwordx4 v[194:197], v144, s[20:21] offset:512
	global_load_dwordx4 v[198:201], v210, s[22:23] offset:512
	global_load_dwordx4 v[202:205], v210, s[38:39] offset:512
	global_load_dwordx4 v[206:209], v210, s[16:17] offset:512
	global_load_dwordx4 v[82:85], v144, s[20:21] offset:576
	global_load_dwordx4 v[86:89], v210, s[22:23] offset:576
	global_load_dwordx4 v[90:93], v210, s[38:39] offset:576
	global_load_dwordx4 v[94:97], v210, s[16:17] offset:576
	global_load_dwordx4 v[66:69], v145, s[20:21]
	global_load_dwordx4 v[70:73], v211, s[22:23]
	global_load_dwordx4 v[74:77], v211, s[38:39]
	global_load_dwordx4 v[78:81], v211, s[16:17]
	global_load_dwordx4 v[50:53], v145, s[20:21] offset:64
	global_load_dwordx4 v[54:57], v211, s[22:23] offset:64
	global_load_dwordx4 v[58:61], v211, s[38:39] offset:64
	global_load_dwordx4 v[62:65], v211, s[16:17] offset:64
	global_load_dwordx4 v[34:37], v145, s[20:21] offset:512
	global_load_dwordx4 v[38:41], v211, s[22:23] offset:512
	global_load_dwordx4 v[42:45], v211, s[38:39] offset:512
	global_load_dwordx4 v[46:49], v211, s[16:17] offset:512
	global_load_dwordx4 v[18:21], v145, s[20:21] offset:576
	global_load_dwordx4 v[22:25], v211, s[22:23] offset:576
	global_load_dwordx4 v[26:29], v211, s[38:39] offset:576
	global_load_dwordx4 v[30:33], v211, s[16:17] offset:576
	s_waitcnt vmcnt(28)
	v_pk_fma_f32 v[126:127], v[126:127], v[146:147], v[162:163]
	v_pk_fma_f32 v[128:129], v[128:129], v[148:149], v[164:165]
	v_pk_add_f32 v[126:127], v[126:127], v[166:167]
	v_pk_add_f32 v[128:129], v[128:129], v[168:169]
	v_pk_add_f32 v[126:127], v[126:127], v[170:171]
	v_pk_add_f32 v[128:129], v[128:129], v[172:173]
	v_pk_add_f32 v[126:127], v[126:127], v[174:175]
	v_pk_add_f32 v[128:129], v[128:129], v[176:177]
	s_waitcnt vmcnt(24)
	v_pk_fma_f32 v[122:123], v[122:123], v[150:151], v[178:179]
	v_pk_fma_f32 v[124:125], v[124:125], v[152:153], v[180:181]
	v_pk_add_f32 v[122:123], v[122:123], v[182:183]
	v_pk_add_f32 v[124:125], v[124:125], v[184:185]
	v_pk_add_f32 v[122:123], v[122:123], v[186:187]
	v_pk_add_f32 v[124:125], v[124:125], v[188:189]
	v_pk_add_f32 v[122:123], v[122:123], v[190:191]
	v_pk_add_f32 v[124:125], v[124:125], v[192:193]
	s_waitcnt vmcnt(20)
	v_pk_fma_f32 v[118:119], v[118:119], v[154:155], v[194:195]
	v_pk_fma_f32 v[120:121], v[120:121], v[156:157], v[196:197]
	v_pk_add_f32 v[118:119], v[118:119], v[198:199]
	v_pk_add_f32 v[120:121], v[120:121], v[200:201]
	v_pk_add_f32 v[118:119], v[118:119], v[202:203]
	v_pk_add_f32 v[120:121], v[120:121], v[204:205]
	v_pk_add_f32 v[118:119], v[118:119], v[206:207]
	v_pk_add_f32 v[120:121], v[120:121], v[208:209]
	s_waitcnt vmcnt(16)
	v_pk_fma_f32 v[114:115], v[114:115], v[158:159], v[82:83]
	v_pk_fma_f32 v[116:117], v[116:117], v[160:161], v[84:85]
	v_pk_add_f32 v[114:115], v[114:115], v[86:87]
	v_pk_add_f32 v[116:117], v[116:117], v[88:89]
	v_pk_add_f32 v[114:115], v[114:115], v[90:91]
	v_pk_add_f32 v[116:117], v[116:117], v[92:93]
	v_pk_add_f32 v[114:115], v[114:115], v[94:95]
	v_pk_add_f32 v[116:117], v[116:117], v[96:97]
	s_waitcnt vmcnt(12)
	v_pk_fma_f32 v[110:111], v[110:111], v[146:147], v[66:67]
	v_pk_fma_f32 v[112:113], v[112:113], v[148:149], v[68:69]
	v_pk_add_f32 v[110:111], v[110:111], v[70:71]
	v_pk_add_f32 v[112:113], v[112:113], v[72:73]
	v_pk_add_f32 v[110:111], v[110:111], v[74:75]
	v_pk_add_f32 v[112:113], v[112:113], v[76:77]
	v_pk_add_f32 v[110:111], v[110:111], v[78:79]
	v_pk_add_f32 v[112:113], v[112:113], v[80:81]
	s_waitcnt vmcnt(8)
	v_pk_fma_f32 v[106:107], v[106:107], v[150:151], v[50:51]
	v_pk_fma_f32 v[108:109], v[108:109], v[152:153], v[52:53]
	v_pk_add_f32 v[106:107], v[106:107], v[54:55]
	v_pk_add_f32 v[108:109], v[108:109], v[56:57]
	v_pk_add_f32 v[106:107], v[106:107], v[58:59]
	v_pk_add_f32 v[108:109], v[108:109], v[60:61]
	v_pk_add_f32 v[106:107], v[106:107], v[62:63]
	v_pk_add_f32 v[108:109], v[108:109], v[64:65]
	s_waitcnt vmcnt(4)
	v_pk_fma_f32 v[102:103], v[102:103], v[154:155], v[34:35]
	v_pk_fma_f32 v[104:105], v[104:105], v[156:157], v[36:37]
	v_pk_add_f32 v[102:103], v[102:103], v[38:39]
	v_pk_add_f32 v[104:105], v[104:105], v[40:41]
	v_pk_add_f32 v[102:103], v[102:103], v[42:43]
	v_pk_add_f32 v[104:105], v[104:105], v[44:45]
	v_pk_add_f32 v[102:103], v[102:103], v[46:47]
	v_pk_add_f32 v[104:105], v[104:105], v[48:49]
	s_waitcnt vmcnt(0)
	v_pk_fma_f32 v[98:99], v[98:99], v[158:159], v[18:19]
	v_pk_fma_f32 v[100:101], v[100:101], v[160:161], v[20:21]
	v_pk_add_f32 v[98:99], v[98:99], v[22:23]
	v_pk_add_f32 v[100:101], v[100:101], v[24:25]
	v_pk_add_f32 v[98:99], v[98:99], v[26:27]
	v_pk_add_f32 v[100:101], v[100:101], v[28:29]
	v_pk_add_f32 v[98:99], v[98:99], v[30:31]
	v_pk_add_f32 v[100:101], v[100:101], v[32:33]
	global_store_dwordx4 v144, v[126:129], s[20:21]
	global_store_dwordx4 v144, v[122:125], s[20:21] offset:64
	global_store_dwordx4 v144, v[118:121], s[20:21] offset:512
	global_store_dwordx4 v144, v[114:117], s[20:21] offset:576
	global_store_dwordx4 v145, v[110:113], s[20:21]
	global_store_dwordx4 v145, v[106:109], s[20:21] offset:64
	global_store_dwordx4 v145, v[102:105], s[20:21] offset:512
	global_store_dwordx4 v145, v[98:101], s[20:21] offset:576
	s_branch .Lsk_post
;     __device__ __forceinline__ void operator()(const f32x4 (&acc)[2][2][4][2], const pg8::Unit& u, int wr, int wc, int fr, int fq) const {
;     ...
;                 for (int bj = 0; bj < 2; ++bj)
; #pragma unroll
;                     for (int n = 0; n < 2; ++n) { const int c = col0 + bj * 128 + n * 16;
;                         const f32x4 r = *(const f32x4*)(ip + c), g = *(const f32x4*)(gp + c);
;                         *(f32x4*)(op + c) = r + g * acc[ai][bj][m][n]; } }
.Lsk_v1:
	s_waitcnt vmcnt(0)
	s_add_u32 s22, s16, 0x40000
	s_addc_u32 s23, s17, 0
	v_add_u32_e32 v143, 0x0, v142
	v_pk_mul_f32 v[126:127], v[126:127], v[146:147]
	v_pk_mul_f32 v[128:129], v[128:129], v[148:149]
	v_pk_mul_f32 v[122:123], v[122:123], v[150:151]
	v_pk_mul_f32 v[124:125], v[124:125], v[152:153]
	v_pk_mul_f32 v[118:119], v[118:119], v[154:155]
	v_pk_mul_f32 v[120:121], v[120:121], v[156:157]
	v_pk_mul_f32 v[114:115], v[114:115], v[158:159]
	v_pk_mul_f32 v[116:117], v[116:117], v[160:161]
	global_store_dwordx4 v143, v[126:129], s[22:23] sc0 sc1
	global_store_dwordx4 v143, v[122:125], s[22:23] offset:64 sc0 sc1
	global_store_dwordx4 v143, v[118:121], s[22:23] offset:512 sc0 sc1
	global_store_dwordx4 v143, v[114:117], s[22:23] offset:576 sc0 sc1
	v_add_u32_e32 v143, 0x4000, v142
	v_pk_mul_f32 v[110:111], v[110:111], v[146:147]
	v_pk_mul_f32 v[112:113], v[112:113], v[148:149]
	v_pk_mul_f32 v[106:107], v[106:107], v[150:151]
	v_pk_mul_f32 v[108:109], v[108:109], v[152:153]
	v_pk_mul_f32 v[102:103], v[102:103], v[154:155]
	v_pk_mul_f32 v[104:105], v[104:105], v[156:157]
	v_pk_mul_f32 v[98:99], v[98:99], v[158:159]
	v_pk_mul_f32 v[100:101], v[100:101], v[160:161]
	global_store_dwordx4 v143, v[110:113], s[22:23] sc0 sc1
	global_store_dwordx4 v143, v[106:109], s[22:23] offset:64 sc0 sc1
	global_store_dwordx4 v143, v[102:105], s[22:23] offset:512 sc0 sc1
	global_store_dwordx4 v143, v[98:101], s[22:23] offset:576 sc0 sc1
	v_add_u32_e32 v143, 0x20000, v142
	v_pk_mul_f32 v[62:63], v[62:63], v[146:147]
	v_pk_mul_f32 v[64:65], v[64:65], v[148:149]
	v_pk_mul_f32 v[58:59], v[58:59], v[150:151]
	v_pk_mul_f32 v[60:61], v[60:61], v[152:153]
	v_pk_mul_f32 v[54:55], v[54:55], v[154:155]
	v_pk_mul_f32 v[56:57], v[56:57], v[156:157]
	v_pk_mul_f32 v[50:51], v[50:51], v[158:159]
	v_pk_mul_f32 v[52:53], v[52:53], v[160:161]
	global_store_dwordx4 v143, v[62:65], s[22:23] sc0 sc1
	global_store_dwordx4 v143, v[58:61], s[22:23] offset:64 sc0 sc1
	global_store_dwordx4 v143, v[54:57], s[22:23] offset:512 sc0 sc1
	global_store_dwordx4 v143, v[50:53], s[22:23] offset:576 sc0 sc1
	v_add_u32_e32 v143, 0x24000, v142
	v_pk_mul_f32 v[46:47], v[46:47], v[146:147]
	v_pk_mul_f32 v[48:49], v[48:49], v[148:149]
	v_pk_mul_f32 v[42:43], v[42:43], v[150:151]
	v_pk_mul_f32 v[44:45], v[44:45], v[152:153]
	v_pk_mul_f32 v[38:39], v[38:39], v[154:155]
	v_pk_mul_f32 v[40:41], v[40:41], v[156:157]
	v_pk_mul_f32 v[34:35], v[34:35], v[158:159]
	v_pk_mul_f32 v[36:37], v[36:37], v[160:161]
	global_store_dwordx4 v143, v[46:49], s[22:23] sc0 sc1
	global_store_dwordx4 v143, v[42:45], s[22:23] offset:64 sc0 sc1
	global_store_dwordx4 v143, v[38:41], s[22:23] offset:512 sc0 sc1
	global_store_dwordx4 v143, v[34:37], s[22:23] offset:576 sc0 sc1
	v_add_u32_e32 v143, 0x28000, v142
	v_pk_mul_f32 v[30:31], v[30:31], v[146:147]
	v_pk_mul_f32 v[32:33], v[32:33], v[148:149]
	v_pk_mul_f32 v[26:27], v[26:27], v[150:151]
	v_pk_mul_f32 v[28:29], v[28:29], v[152:153]
	v_pk_mul_f32 v[22:23], v[22:23], v[154:155]
	v_pk_mul_f32 v[24:25], v[24:25], v[156:157]
	v_pk_mul_f32 v[18:19], v[18:19], v[158:159]
	v_pk_mul_f32 v[20:21], v[20:21], v[160:161]
	global_store_dwordx4 v143, v[30:33], s[22:23] sc0 sc1
	global_store_dwordx4 v143, v[26:29], s[22:23] offset:64 sc0 sc1
	global_store_dwordx4 v143, v[22:25], s[22:23] offset:512 sc0 sc1
	global_store_dwordx4 v143, v[18:21], s[22:23] offset:576 sc0 sc1
	v_add_u32_e32 v143, 0x2c000, v142
	v_pk_mul_f32 v[14:15], v[14:15], v[146:147]
	v_pk_mul_f32 v[16:17], v[16:17], v[148:149]
	v_pk_mul_f32 v[10:11], v[10:11], v[150:151]
	v_pk_mul_f32 v[12:13], v[12:13], v[152:153]
	v_pk_mul_f32 v[6:7], v[6:7], v[154:155]
	v_pk_mul_f32 v[8:9], v[8:9], v[156:157]
	v_pk_mul_f32 v[2:3], v[2:3], v[158:159]
	v_pk_mul_f32 v[4:5], v[4:5], v[160:161]
	global_store_dwordx4 v143, v[14:17], s[22:23] sc0 sc1
	global_store_dwordx4 v143, v[10:13], s[22:23] offset:64 sc0 sc1
	global_store_dwordx4 v143, v[6:9], s[22:23] offset:512 sc0 sc1
	global_store_dwordx4 v143, v[2:5], s[22:23] offset:576 sc0 sc1
	s_waitcnt vmcnt(0)
	s_mov_b64 s[22:23], exec
	s_mov_b64 exec, 1
	v_mov_b32_e32 v143, 0
	v_mov_b32_e32 v144, 1
	global_atomic_add v143, v144, s[38:39]
	s_mov_b64 exec, s[22:23]
	v_mov_b32_e32 v143, 0
	s_mov_b32 s3, 0

;     __device__ __forceinline__ void operator()(const f32x4 (&acc)[2][2][4][2], const pg8::Unit& u, int wr, int wc, int fr, int fq) const {
;     ...
;                     for (int n = 0; n < 2; ++n) { const int c = col0 + bj * 128 + n * 16;
;                         const f32x4 r = *(const f32x4*)(ip + c), g = *(const f32x4*)(gp + c);
;                         *(f32x4*)(op + c) = r + g * acc[ai][bj][m][n]; } }
.Lsk_spun1:
	buffer_inv sc1
	s_waitcnt vmcnt(0)
	s_add_u32 s22, s16, 0x0
	s_addc_u32 s23, s17, 0
	s_add_u32 s38, s16, 0x80000
	s_addc_u32 s39, s17, 0
	s_add_u32 s16, s16, 0xc0000
	s_addc_u32 s17, s17, 0
	v_add_u32_e32 v144, 0x40000, v136
	v_add_u32_e32 v210, 0x8000, v142
	v_add_u32_e32 v145, 0x60000, v136
	v_add_u32_e32 v211, 0xc000, v142
	global_load_dwordx4 v[162:165], v144, s[20:21]
	global_load_dwordx4 v[166:169], v210, s[22:23]
	global_load_dwordx4 v[170:173], v210, s[38:39]
	global_load_dwordx4 v[174:177], v210, s[16:17]
	global_load_dwordx4 v[178:181], v144, s[20:21] offset:64
	global_load_dwordx4 v[182:185], v210, s[22:23] offset:64
	global_load_dwordx4 v[186:189], v210, s[38:39] offset:64
	global_load_dwordx4 v[190:193], v210, s[16:17] offset:64
	global_load_dwordx4 v[194:197], v144, s[20:21] offset:512
	global_load_dwordx4 v[198:201], v210, s[22:23] offset:512
	global_load_dwordx4 v[202:205], v210, s[38:39] offset:512
	global_load_dwordx4 v[206:209], v210, s[16:17] offset:512
	global_load_dwordx4 v[114:117], v144, s[20:21] offset:576
	global_load_dwordx4 v[118:121], v210, s[22:23] offset:576
	global_load_dwordx4 v[122:125], v210, s[38:39] offset:576
	global_load_dwordx4 v[126:129], v210, s[16:17] offset:576
	global_load_dwordx4 v[98:101], v145, s[20:21]
	global_load_dwordx4 v[102:105], v211, s[22:23]
	global_load_dwordx4 v[106:109], v211, s[38:39]
	global_load_dwordx4 v[110:113], v211, s[16:17]
	global_load_dwordx4 v[50:53], v145, s[20:21] offset:64
	global_load_dwordx4 v[54:57], v211, s[22:23] offset:64
	global_load_dwordx4 v[58:61], v211, s[38:39] offset:64
	global_load_dwordx4 v[62:65], v211, s[16:17] offset:64
	global_load_dwordx4 v[34:37], v145, s[20:21] offset:512
	global_load_dwordx4 v[38:41], v211, s[22:23] offset:512
	global_load_dwordx4 v[42:45], v211, s[38:39] offset:512
	global_load_dwordx4 v[46:49], v211, s[16:17] offset:512
	global_load_dwordx4 v[18:21], v145, s[20:21] offset:576
	global_load_dwordx4 v[22:25], v211, s[22:23] offset:576
	global_load_dwordx4 v[26:29], v211, s[38:39] offset:576
	global_load_dwordx4 v[30:33], v211, s[16:17] offset:576
	s_waitcnt vmcnt(28)
	v_pk_fma_f32 v[94:95], v[94:95], v[146:147], v[162:163]
	v_pk_fma_f32 v[96:97], v[96:97], v[148:149], v[164:165]
	v_pk_add_f32 v[94:95], v[94:95], v[166:167]
	v_pk_add_f32 v[96:97], v[96:97], v[168:169]
	v_pk_add_f32 v[94:95], v[94:95], v[170:171]
	v_pk_add_f32 v[96:97], v[96:97], v[172:173]
	v_pk_add_f32 v[94:95], v[94:95], v[174:175]
	v_pk_add_f32 v[96:97], v[96:97], v[176:177]
	s_waitcnt vmcnt(24)
	v_pk_fma_f32 v[90:91], v[90:91], v[150:151], v[178:179]
	v_pk_fma_f32 v[92:93], v[92:93], v[152:153], v[180:181]
	v_pk_add_f32 v[90:91], v[90:91], v[182:183]
	v_pk_add_f32 v[92:93], v[92:93], v[184:185]
	v_pk_add_f32 v[90:91], v[90:91], v[186:187]
	v_pk_add_f32 v[92:93], v[92:93], v[188:189]
	v_pk_add_f32 v[90:91], v[90:91], v[190:191]
	v_pk_add_f32 v[92:93], v[92:93], v[192:193]
	s_waitcnt vmcnt(20)
	v_pk_fma_f32 v[86:87], v[86:87], v[154:155], v[194:195]
	v_pk_fma_f32 v[88:89], v[88:89], v[156:157], v[196:197]
	v_pk_add_f32 v[86:87], v[86:87], v[198:199]
	v_pk_add_f32 v[88:89], v[88:89], v[200:201]
	v_pk_add_f32 v[86:87], v[86:87], v[202:203]
	v_pk_add_f32 v[88:89], v[88:89], v[204:205]
	v_pk_add_f32 v[86:87], v[86:87], v[206:207]
	v_pk_add_f32 v[88:89], v[88:89], v[208:209]
	s_waitcnt vmcnt(16)
	v_pk_fma_f32 v[82:83], v[82:83], v[158:159], v[114:115]
	v_pk_fma_f32 v[84:85], v[84:85], v[160:161], v[116:117]
	v_pk_add_f32 v[82:83], v[82:83], v[118:119]
	v_pk_add_f32 v[84:85], v[84:85], v[120:121]
	v_pk_add_f32 v[82:83], v[82:83], v[122:123]
	v_pk_add_f32 v[84:85], v[84:85], v[124:125]
	v_pk_add_f32 v[82:83], v[82:83], v[126:127]
	v_pk_add_f32 v[84:85], v[84:85], v[128:129]
	s_waitcnt vmcnt(12)
	v_pk_fma_f32 v[78:79], v[78:79], v[146:147], v[98:99]
	v_pk_fma_f32 v[80:81], v[80:81], v[148:149], v[100:101]
	v_pk_add_f32 v[78:79], v[78:79], v[102:103]
	v_pk_add_f32 v[80:81], v[80:81], v[104:105]
	v_pk_add_f32 v[78:79], v[78:79], v[106:107]
	v_pk_add_f32 v[80:81], v[80:81], v[108:109]
	v_pk_add_f32 v[78:79], v[78:79], v[110:111]
	v_pk_add_f32 v[80:81], v[80:81], v[112:113]
	s_waitcnt vmcnt(8)
	v_pk_fma_f32 v[74:75], v[74:75], v[150:151], v[50:51]
	v_pk_fma_f32 v[76:77], v[76:77], v[152:153], v[52:53]
	v_pk_add_f32 v[74:75], v[74:75], v[54:55]
	v_pk_add_f32 v[76:77], v[76:77], v[56:57]
	v_pk_add_f32 v[74:75], v[74:75], v[58:59]
	v_pk_add_f32 v[76:77], v[76:77], v[60:61]
	v_pk_add_f32 v[74:75], v[74:75], v[62:63]
	v_pk_add_f32 v[76:77], v[76:77], v[64:65]
	s_waitcnt vmcnt(4)
	v_pk_fma_f32 v[70:71], v[70:71], v[154:155], v[34:35]
	v_pk_fma_f32 v[72:73], v[72:73], v[156:157], v[36:37]
	v_pk_add_f32 v[70:71], v[70:71], v[38:39]
	v_pk_add_f32 v[72:73], v[72:73], v[40:41]
	v_pk_add_f32 v[70:71], v[70:71], v[42:43]
	v_pk_add_f32 v[72:73], v[72:73], v[44:45]
	v_pk_add_f32 v[70:71], v[70:71], v[46:47]
	v_pk_add_f32 v[72:73], v[72:73], v[48:49]
	s_waitcnt vmcnt(0)
	v_pk_fma_f32 v[66:67], v[66:67], v[158:159], v[18:19]
	v_pk_fma_f32 v[68:69], v[68:69], v[160:161], v[20:21]
	v_pk_add_f32 v[66:67], v[66:67], v[22:23]
	v_pk_add_f32 v[68:69], v[68:69], v[24:25]
	v_pk_add_f32 v[66:67], v[66:67], v[26:27]
	v_pk_add_f32 v[68:69], v[68:69], v[28:29]
	v_pk_add_f32 v[66:67], v[66:67], v[30:31]
	v_pk_add_f32 v[68:69], v[68:69], v[32:33]
	global_store_dwordx4 v144, v[94:97], s[20:21]
	global_store_dwordx4 v144, v[90:93], s[20:21] offset:64
	global_store_dwordx4 v144, v[86:89], s[20:21] offset:512
	global_store_dwordx4 v144, v[82:85], s[20:21] offset:576
	global_store_dwordx4 v145, v[78:81], s[20:21]
	global_store_dwordx4 v145, v[74:77], s[20:21] offset:64
	global_store_dwordx4 v145, v[70:73], s[20:21] offset:512
	global_store_dwordx4 v145, v[66:69], s[20:21] offset:576
	s_branch .Lsk_post
;     __device__ __forceinline__ void operator()(const f32x4 (&acc)[2][2][4][2], const pg8::Unit& u, int wr, int wc, int fr, int fq) const {
;     ...
;                 for (int bj = 0; bj < 2; ++bj)
; #pragma unroll
;                     for (int n = 0; n < 2; ++n) { const int c = col0 + bj * 128 + n * 16;
;                         const f32x4 r = *(const f32x4*)(ip + c), g = *(const f32x4*)(gp + c);
;                         *(f32x4*)(op + c) = r + g * acc[ai][bj][m][n]; } }
.Lsk_v2:
	s_waitcnt vmcnt(0)
	s_add_u32 s22, s16, 0x80000
	s_addc_u32 s23, s17, 0
	v_add_u32_e32 v143, 0x0, v142
	v_pk_mul_f32 v[126:127], v[126:127], v[146:147]
	v_pk_mul_f32 v[128:129], v[128:129], v[148:149]
	v_pk_mul_f32 v[122:123], v[122:123], v[150:151]
	v_pk_mul_f32 v[124:125], v[124:125], v[152:153]
	v_pk_mul_f32 v[118:119], v[118:119], v[154:155]
	v_pk_mul_f32 v[120:121], v[120:121], v[156:157]
	v_pk_mul_f32 v[114:115], v[114:115], v[158:159]
	v_pk_mul_f32 v[116:117], v[116:117], v[160:161]
	global_store_dwordx4 v143, v[126:129], s[22:23] sc0 sc1
	global_store_dwordx4 v143, v[122:125], s[22:23] offset:64 sc0 sc1
	global_store_dwordx4 v143, v[118:121], s[22:23] offset:512 sc0 sc1
	global_store_dwordx4 v143, v[114:117], s[22:23] offset:576 sc0 sc1
	v_add_u32_e32 v143, 0x4000, v142
	v_pk_mul_f32 v[110:111], v[110:111], v[146:147]
	v_pk_mul_f32 v[112:113], v[112:113], v[148:149]
	v_pk_mul_f32 v[106:107], v[106:107], v[150:151]
	v_pk_mul_f32 v[108:109], v[108:109], v[152:153]
	v_pk_mul_f32 v[102:103], v[102:103], v[154:155]
	v_pk_mul_f32 v[104:105], v[104:105], v[156:157]
	v_pk_mul_f32 v[98:99], v[98:99], v[158:159]
	v_pk_mul_f32 v[100:101], v[100:101], v[160:161]
	global_store_dwordx4 v143, v[110:113], s[22:23] sc0 sc1
	global_store_dwordx4 v143, v[106:109], s[22:23] offset:64 sc0 sc1
	global_store_dwordx4 v143, v[102:105], s[22:23] offset:512 sc0 sc1
	global_store_dwordx4 v143, v[98:101], s[22:23] offset:576 sc0 sc1
	v_add_u32_e32 v143, 0x8000, v142
	v_pk_mul_f32 v[94:95], v[94:95], v[146:147]
	v_pk_mul_f32 v[96:97], v[96:97], v[148:149]
	v_pk_mul_f32 v[90:91], v[90:91], v[150:151]
	v_pk_mul_f32 v[92:93], v[92:93], v[152:153]
	v_pk_mul_f32 v[86:87], v[86:87], v[154:155]
	v_pk_mul_f32 v[88:89], v[88:89], v[156:157]
	v_pk_mul_f32 v[82:83], v[82:83], v[158:159]
	v_pk_mul_f32 v[84:85], v[84:85], v[160:161]
	global_store_dwordx4 v143, v[94:97], s[22:23] sc0 sc1
	global_store_dwordx4 v143, v[90:93], s[22:23] offset:64 sc0 sc1
	global_store_dwordx4 v143, v[86:89], s[22:23] offset:512 sc0 sc1
	global_store_dwordx4 v143, v[82:85], s[22:23] offset:576 sc0 sc1
	v_add_u32_e32 v143, 0xc000, v142
	v_pk_mul_f32 v[78:79], v[78:79], v[146:147]
	v_pk_mul_f32 v[80:81], v[80:81], v[148:149]
	v_pk_mul_f32 v[74:75], v[74:75], v[150:151]
	v_pk_mul_f32 v[76:77], v[76:77], v[152:153]
	v_pk_mul_f32 v[70:71], v[70:71], v[154:155]
	v_pk_mul_f32 v[72:73], v[72:73], v[156:157]
	v_pk_mul_f32 v[66:67], v[66:67], v[158:159]
	v_pk_mul_f32 v[68:69], v[68:69], v[160:161]
	global_store_dwordx4 v143, v[78:81], s[22:23] sc0 sc1
	global_store_dwordx4 v143, v[74:77], s[22:23] offset:64 sc0 sc1
	global_store_dwordx4 v143, v[70:73], s[22:23] offset:512 sc0 sc1
	global_store_dwordx4 v143, v[66:69], s[22:23] offset:576 sc0 sc1
	v_add_u32_e32 v143, 0x28000, v142
	v_pk_mul_f32 v[30:31], v[30:31], v[146:147]
	v_pk_mul_f32 v[32:33], v[32:33], v[148:149]
	v_pk_mul_f32 v[26:27], v[26:27], v[150:151]
	v_pk_mul_f32 v[28:29], v[28:29], v[152:153]
	v_pk_mul_f32 v[22:23], v[22:23], v[154:155]
	v_pk_mul_f32 v[24:25], v[24:25], v[156:157]
	v_pk_mul_f32 v[18:19], v[18:19], v[158:159]
	v_pk_mul_f32 v[20:21], v[20:21], v[160:161]
	global_store_dwordx4 v143, v[30:33], s[22:23] sc0 sc1
	global_store_dwordx4 v143, v[26:29], s[22:23] offset:64 sc0 sc1
	global_store_dwordx4 v143, v[22:25], s[22:23] offset:512 sc0 sc1
	global_store_dwordx4 v143, v[18:21], s[22:23] offset:576 sc0 sc1
	v_add_u32_e32 v143, 0x2c000, v142
	v_pk_mul_f32 v[14:15], v[14:15], v[146:147]
	v_pk_mul_f32 v[16:17], v[16:17], v[148:149]
	v_pk_mul_f32 v[10:11], v[10:11], v[150:151]
	v_pk_mul_f32 v[12:13], v[12:13], v[152:153]
	v_pk_mul_f32 v[6:7], v[6:7], v[154:155]
	v_pk_mul_f32 v[8:9], v[8:9], v[156:157]
	v_pk_mul_f32 v[2:3], v[2:3], v[158:159]
	v_pk_mul_f32 v[4:5], v[4:5], v[160:161]
	global_store_dwordx4 v143, v[14:17], s[22:23] sc0 sc1
	global_store_dwordx4 v143, v[10:13], s[22:23] offset:64 sc0 sc1
	global_store_dwordx4 v143, v[6:9], s[22:23] offset:512 sc0 sc1
	global_store_dwordx4 v143, v[2:5], s[22:23] offset:576 sc0 sc1
	s_waitcnt vmcnt(0)
	s_mov_b64 s[22:23], exec
	s_mov_b64 exec, 1
	v_mov_b32_e32 v143, 0
	v_mov_b32_e32 v144, 1
	global_atomic_add v143, v144, s[38:39]
	s_mov_b64 exec, s[22:23]
	v_mov_b32_e32 v143, 0
	s_mov_b32 s3, 0

;     __device__ __forceinline__ void operator()(const f32x4 (&acc)[2][2][4][2], const pg8::Unit& u, int wr, int wc, int fr, int fq) const {
;     ...
;                     for (int n = 0; n < 2; ++n) { const int c = col0 + bj * 128 + n * 16;
;                         const f32x4 r = *(const f32x4*)(ip + c), g = *(const f32x4*)(gp + c);
;                         *(f32x4*)(op + c) = r + g * acc[ai][bj][m][n]; } }
.Lsk_spun2:
	buffer_inv sc1
	s_waitcnt vmcnt(0)
	s_add_u32 s22, s16, 0x0
	s_addc_u32 s23, s17, 0
	s_add_u32 s38, s16, 0x40000
	s_addc_u32 s39, s17, 0
	s_add_u32 s16, s16, 0xc0000
	s_addc_u32 s17, s17, 0
	v_add_u32_e32 v144, 0x100000, v136
	v_add_u32_e32 v210, 0x20000, v142
	v_add_u32_e32 v145, 0x120000, v136
	v_add_u32_e32 v211, 0x24000, v142
	global_load_dwordx4 v[162:165], v144, s[20:21]
	global_load_dwordx4 v[166:169], v210, s[22:23]
	global_load_dwordx4 v[170:173], v210, s[38:39]
	global_load_dwordx4 v[174:177], v210, s[16:17]
	global_load_dwordx4 v[178:181], v144, s[20:21] offset:64
	global_load_dwordx4 v[182:185], v210, s[22:23] offset:64
	global_load_dwordx4 v[186:189], v210, s[38:39] offset:64
	global_load_dwordx4 v[190:193], v210, s[16:17] offset:64
	global_load_dwordx4 v[194:197], v144, s[20:21] offset:512
	global_load_dwordx4 v[198:201], v210, s[22:23] offset:512
	global_load_dwordx4 v[202:205], v210, s[38:39] offset:512
	global_load_dwordx4 v[206:209], v210, s[16:17] offset:512
	global_load_dwordx4 v[114:117], v144, s[20:21] offset:576
	global_load_dwordx4 v[118:121], v210, s[22:23] offset:576
	global_load_dwordx4 v[122:125], v210, s[38:39] offset:576
	global_load_dwordx4 v[126:129], v210, s[16:17] offset:576
	global_load_dwordx4 v[98:101], v145, s[20:21]
	global_load_dwordx4 v[102:105], v211, s[22:23]
	global_load_dwordx4 v[106:109], v211, s[38:39]
	global_load_dwordx4 v[110:113], v211, s[16:17]
	global_load_dwordx4 v[82:85], v145, s[20:21] offset:64
	global_load_dwordx4 v[86:89], v211, s[22:23] offset:64
	global_load_dwordx4 v[90:93], v211, s[38:39] offset:64
	global_load_dwordx4 v[94:97], v211, s[16:17] offset:64
	global_load_dwordx4 v[66:69], v145, s[20:21] offset:512
	global_load_dwordx4 v[70:73], v211, s[22:23] offset:512
	global_load_dwordx4 v[74:77], v211, s[38:39] offset:512
	global_load_dwordx4 v[78:81], v211, s[16:17] offset:512
	global_load_dwordx4 v[18:21], v145, s[20:21] offset:576
	global_load_dwordx4 v[22:25], v211, s[22:23] offset:576
	global_load_dwordx4 v[26:29], v211, s[38:39] offset:576
	global_load_dwordx4 v[30:33], v211, s[16:17] offset:576
	s_waitcnt vmcnt(28)
	v_pk_fma_f32 v[62:63], v[62:63], v[146:147], v[162:163]
	v_pk_fma_f32 v[64:65], v[64:65], v[148:149], v[164:165]
	v_pk_add_f32 v[62:63], v[62:63], v[166:167]
	v_pk_add_f32 v[64:65], v[64:65], v[168:169]
	v_pk_add_f32 v[62:63], v[62:63], v[170:171]
	v_pk_add_f32 v[64:65], v[64:65], v[172:173]
	v_pk_add_f32 v[62:63], v[62:63], v[174:175]
	v_pk_add_f32 v[64:65], v[64:65], v[176:177]
	s_waitcnt vmcnt(24)
	v_pk_fma_f32 v[58:59], v[58:59], v[150:151], v[178:179]
	v_pk_fma_f32 v[60:61], v[60:61], v[152:153], v[180:181]
	v_pk_add_f32 v[58:59], v[58:59], v[182:183]
	v_pk_add_f32 v[60:61], v[60:61], v[184:185]
	v_pk_add_f32 v[58:59], v[58:59], v[186:187]
	v_pk_add_f32 v[60:61], v[60:61], v[188:189]
	v_pk_add_f32 v[58:59], v[58:59], v[190:191]
	v_pk_add_f32 v[60:61], v[60:61], v[192:193]
	s_waitcnt vmcnt(20)
	v_pk_fma_f32 v[54:55], v[54:55], v[154:155], v[194:195]
	v_pk_fma_f32 v[56:57], v[56:57], v[156:157], v[196:197]
	v_pk_add_f32 v[54:55], v[54:55], v[198:199]
	v_pk_add_f32 v[56:57], v[56:57], v[200:201]
	v_pk_add_f32 v[54:55], v[54:55], v[202:203]
	v_pk_add_f32 v[56:57], v[56:57], v[204:205]
	v_pk_add_f32 v[54:55], v[54:55], v[206:207]
	v_pk_add_f32 v[56:57], v[56:57], v[208:209]
	s_waitcnt vmcnt(16)
	v_pk_fma_f32 v[50:51], v[50:51], v[158:159], v[114:115]
	v_pk_fma_f32 v[52:53], v[52:53], v[160:161], v[116:117]
	v_pk_add_f32 v[50:51], v[50:51], v[118:119]
	v_pk_add_f32 v[52:53], v[52:53], v[120:121]
	v_pk_add_f32 v[50:51], v[50:51], v[122:123]
	v_pk_add_f32 v[52:53], v[52:53], v[124:125]
	v_pk_add_f32 v[50:51], v[50:51], v[126:127]
	v_pk_add_f32 v[52:53], v[52:53], v[128:129]
	s_waitcnt vmcnt(12)
	v_pk_fma_f32 v[46:47], v[46:47], v[146:147], v[98:99]
	v_pk_fma_f32 v[48:49], v[48:49], v[148:149], v[100:101]
	v_pk_add_f32 v[46:47], v[46:47], v[102:103]
	v_pk_add_f32 v[48:49], v[48:49], v[104:105]
	v_pk_add_f32 v[46:47], v[46:47], v[106:107]
	v_pk_add_f32 v[48:49], v[48:49], v[108:109]
	v_pk_add_f32 v[46:47], v[46:47], v[110:111]
	v_pk_add_f32 v[48:49], v[48:49], v[112:113]
	s_waitcnt vmcnt(8)
	v_pk_fma_f32 v[42:43], v[42:43], v[150:151], v[82:83]
	v_pk_fma_f32 v[44:45], v[44:45], v[152:153], v[84:85]
	v_pk_add_f32 v[42:43], v[42:43], v[86:87]
	v_pk_add_f32 v[44:45], v[44:45], v[88:89]
	v_pk_add_f32 v[42:43], v[42:43], v[90:91]
	v_pk_add_f32 v[44:45], v[44:45], v[92:93]
	v_pk_add_f32 v[42:43], v[42:43], v[94:95]
	v_pk_add_f32 v[44:45], v[44:45], v[96:97]
	s_waitcnt vmcnt(4)
	v_pk_fma_f32 v[38:39], v[38:39], v[154:155], v[66:67]
	v_pk_fma_f32 v[40:41], v[40:41], v[156:157], v[68:69]
	v_pk_add_f32 v[38:39], v[38:39], v[70:71]
	v_pk_add_f32 v[40:41], v[40:41], v[72:73]
	v_pk_add_f32 v[38:39], v[38:39], v[74:75]
	v_pk_add_f32 v[40:41], v[40:41], v[76:77]
	v_pk_add_f32 v[38:39], v[38:39], v[78:79]
	v_pk_add_f32 v[40:41], v[40:41], v[80:81]
	s_waitcnt vmcnt(0)
	v_pk_fma_f32 v[34:35], v[34:35], v[158:159], v[18:19]
	v_pk_fma_f32 v[36:37], v[36:37], v[160:161], v[20:21]
	v_pk_add_f32 v[34:35], v[34:35], v[22:23]
	v_pk_add_f32 v[36:37], v[36:37], v[24:25]
	v_pk_add_f32 v[34:35], v[34:35], v[26:27]
	v_pk_add_f32 v[36:37], v[36:37], v[28:29]
	v_pk_add_f32 v[34:35], v[34:35], v[30:31]
	v_pk_add_f32 v[36:37], v[36:37], v[32:33]
	global_store_dwordx4 v144, v[62:65], s[20:21]
	global_store_dwordx4 v144, v[58:61], s[20:21] offset:64
	global_store_dwordx4 v144, v[54:57], s[20:21] offset:512
	global_store_dwordx4 v144, v[50:53], s[20:21] offset:576
	global_store_dwordx4 v145, v[46:49], s[20:21]
	global_store_dwordx4 v145, v[42:45], s[20:21] offset:64
	global_store_dwordx4 v145, v[38:41], s[20:21] offset:512
	global_store_dwordx4 v145, v[34:37], s[20:21] offset:576
	s_branch .Lsk_post
;     __device__ __forceinline__ void operator()(const f32x4 (&acc)[2][2][4][2], const pg8::Unit& u, int wr, int wc, int fr, int fq) const {
;     ...
;                 for (int bj = 0; bj < 2; ++bj)
; #pragma unroll
;                     for (int n = 0; n < 2; ++n) { const int c = col0 + bj * 128 + n * 16;
;                         const f32x4 r = *(const f32x4*)(ip + c), g = *(const f32x4*)(gp + c);
;                         *(f32x4*)(op + c) = r + g * acc[ai][bj][m][n]; } }
.Lsk_v3:
	s_waitcnt vmcnt(0)
	s_add_u32 s22, s16, 0xc0000
	s_addc_u32 s23, s17, 0
	v_add_u32_e32 v143, 0x0, v142
	v_pk_mul_f32 v[126:127], v[126:127], v[146:147]
	v_pk_mul_f32 v[128:129], v[128:129], v[148:149]
	v_pk_mul_f32 v[122:123], v[122:123], v[150:151]
	v_pk_mul_f32 v[124:125], v[124:125], v[152:153]
	v_pk_mul_f32 v[118:119], v[118:119], v[154:155]
	v_pk_mul_f32 v[120:121], v[120:121], v[156:157]
	v_pk_mul_f32 v[114:115], v[114:115], v[158:159]
	v_pk_mul_f32 v[116:117], v[116:117], v[160:161]
	global_store_dwordx4 v143, v[126:129], s[22:23] sc0 sc1
	global_store_dwordx4 v143, v[122:125], s[22:23] offset:64 sc0 sc1
	global_store_dwordx4 v143, v[118:121], s[22:23] offset:512 sc0 sc1
	global_store_dwordx4 v143, v[114:117], s[22:23] offset:576 sc0 sc1
	v_add_u32_e32 v143, 0x4000, v142
	v_pk_mul_f32 v[110:111], v[110:111], v[146:147]
	v_pk_mul_f32 v[112:113], v[112:113], v[148:149]
	v_pk_mul_f32 v[106:107], v[106:107], v[150:151]
	v_pk_mul_f32 v[108:109], v[108:109], v[152:153]
	v_pk_mul_f32 v[102:103], v[102:103], v[154:155]
	v_pk_mul_f32 v[104:105], v[104:105], v[156:157]
	v_pk_mul_f32 v[98:99], v[98:99], v[158:159]
	v_pk_mul_f32 v[100:101], v[100:101], v[160:161]
	global_store_dwordx4 v143, v[110:113], s[22:23] sc0 sc1
	global_store_dwordx4 v143, v[106:109], s[22:23] offset:64 sc0 sc1
	global_store_dwordx4 v143, v[102:105], s[22:23] offset:512 sc0 sc1
	global_store_dwordx4 v143, v[98:101], s[22:23] offset:576 sc0 sc1
	v_add_u32_e32 v143, 0x8000, v142
	v_pk_mul_f32 v[94:95], v[94:95], v[146:147]
	v_pk_mul_f32 v[96:97], v[96:97], v[148:149]
	v_pk_mul_f32 v[90:91], v[90:91], v[150:151]
	v_pk_mul_f32 v[92:93], v[92:93], v[152:153]
	v_pk_mul_f32 v[86:87], v[86:87], v[154:155]
	v_pk_mul_f32 v[88:89], v[88:89], v[156:157]
	v_pk_mul_f32 v[82:83], v[82:83], v[158:159]
	v_pk_mul_f32 v[84:85], v[84:85], v[160:161]
	global_store_dwordx4 v143, v[94:97], s[22:23] sc0 sc1
	global_store_dwordx4 v143, v[90:93], s[22:23] offset:64 sc0 sc1
	global_store_dwordx4 v143, v[86:89], s[22:23] offset:512 sc0 sc1
	global_store_dwordx4 v143, v[82:85], s[22:23] offset:576 sc0 sc1
	v_add_u32_e32 v143, 0xc000, v142
	v_pk_mul_f32 v[78:79], v[78:79], v[146:147]
	v_pk_mul_f32 v[80:81], v[80:81], v[148:149]
	v_pk_mul_f32 v[74:75], v[74:75], v[150:151]
	v_pk_mul_f32 v[76:77], v[76:77], v[152:153]
	v_pk_mul_f32 v[70:71], v[70:71], v[154:155]
	v_pk_mul_f32 v[72:73], v[72:73], v[156:157]
	v_pk_mul_f32 v[66:67], v[66:67], v[158:159]
	v_pk_mul_f32 v[68:69], v[68:69], v[160:161]
	global_store_dwordx4 v143, v[78:81], s[22:23] sc0 sc1
	global_store_dwordx4 v143, v[74:77], s[22:23] offset:64 sc0 sc1
	global_store_dwordx4 v143, v[70:73], s[22:23] offset:512 sc0 sc1
	global_store_dwordx4 v143, v[66:69], s[22:23] offset:576 sc0 sc1
	v_add_u32_e32 v143, 0x20000, v142
	v_pk_mul_f32 v[62:63], v[62:63], v[146:147]
	v_pk_mul_f32 v[64:65], v[64:65], v[148:149]
	v_pk_mul_f32 v[58:59], v[58:59], v[150:151]
	v_pk_mul_f32 v[60:61], v[60:61], v[152:153]
	v_pk_mul_f32 v[54:55], v[54:55], v[154:155]
	v_pk_mul_f32 v[56:57], v[56:57], v[156:157]
	v_pk_mul_f32 v[50:51], v[50:51], v[158:159]
	v_pk_mul_f32 v[52:53], v[52:53], v[160:161]
	global_store_dwordx4 v143, v[62:65], s[22:23] sc0 sc1
	global_store_dwordx4 v143, v[58:61], s[22:23] offset:64 sc0 sc1
	global_store_dwordx4 v143, v[54:57], s[22:23] offset:512 sc0 sc1
	global_store_dwordx4 v143, v[50:53], s[22:23] offset:576 sc0 sc1
	v_add_u32_e32 v143, 0x24000, v142
	v_pk_mul_f32 v[46:47], v[46:47], v[146:147]
	v_pk_mul_f32 v[48:49], v[48:49], v[148:149]
	v_pk_mul_f32 v[42:43], v[42:43], v[150:151]
	v_pk_mul_f32 v[44:45], v[44:45], v[152:153]
	v_pk_mul_f32 v[38:39], v[38:39], v[154:155]
	v_pk_mul_f32 v[40:41], v[40:41], v[156:157]
	v_pk_mul_f32 v[34:35], v[34:35], v[158:159]
	v_pk_mul_f32 v[36:37], v[36:37], v[160:161]
	global_store_dwordx4 v143, v[46:49], s[22:23] sc0 sc1
	global_store_dwordx4 v143, v[42:45], s[22:23] offset:64 sc0 sc1
	global_store_dwordx4 v143, v[38:41], s[22:23] offset:512 sc0 sc1
	global_store_dwordx4 v143, v[34:37], s[22:23] offset:576 sc0 sc1
	s_waitcnt vmcnt(0)
	s_mov_b64 s[22:23], exec
	s_mov_b64 exec, 1
	v_mov_b32_e32 v143, 0
	v_mov_b32_e32 v144, 1
	global_atomic_add v143, v144, s[38:39]
	s_mov_b64 exec, s[22:23]
	v_mov_b32_e32 v143, 0
	s_mov_b32 s3, 0

;     __device__ __forceinline__ void operator()(const f32x4 (&acc)[2][2][4][2], const pg8::Unit& u, int wr, int wc, int fr, int fq) const {
;     ...
;                     for (int n = 0; n < 2; ++n) { const int c = col0 + bj * 128 + n * 16;
;                         const f32x4 r = *(const f32x4*)(ip + c), g = *(const f32x4*)(gp + c);
;                         *(f32x4*)(op + c) = r + g * acc[ai][bj][m][n]; } }
.Lsk_spun3:
	buffer_inv sc1
	s_waitcnt vmcnt(0)
	s_add_u32 s22, s16, 0x0
	s_addc_u32 s23, s17, 0
	s_add_u32 s38, s16, 0x40000
	s_addc_u32 s39, s17, 0
	s_add_u32 s16, s16, 0x80000
	s_addc_u32 s17, s17, 0
	v_add_u32_e32 v144, 0x140000, v136
	v_add_u32_e32 v210, 0x28000, v142
	v_add_u32_e32 v145, 0x160000, v136
	v_add_u32_e32 v211, 0x2c000, v142
	global_load_dwordx4 v[162:165], v144, s[20:21]
	global_load_dwordx4 v[166:169], v210, s[22:23]
	global_load_dwordx4 v[170:173], v210, s[38:39]
	global_load_dwordx4 v[174:177], v210, s[16:17]
	global_load_dwordx4 v[178:181], v144, s[20:21] offset:64
	global_load_dwordx4 v[182:185], v210, s[22:23] offset:64
	global_load_dwordx4 v[186:189], v210, s[38:39] offset:64
	global_load_dwordx4 v[190:193], v210, s[16:17] offset:64
	global_load_dwordx4 v[194:197], v144, s[20:21] offset:512
	global_load_dwordx4 v[198:201], v210, s[22:23] offset:512
	global_load_dwordx4 v[202:205], v210, s[38:39] offset:512
	global_load_dwordx4 v[206:209], v210, s[16:17] offset:512
	global_load_dwordx4 v[114:117], v144, s[20:21] offset:576
	global_load_dwordx4 v[118:121], v210, s[22:23] offset:576
	global_load_dwordx4 v[122:125], v210, s[38:39] offset:576
	global_load_dwordx4 v[126:129], v210, s[16:17] offset:576
	global_load_dwordx4 v[98:101], v145, s[20:21]
	global_load_dwordx4 v[102:105], v211, s[22:23]
	global_load_dwordx4 v[106:109], v211, s[38:39]
	global_load_dwordx4 v[110:113], v211, s[16:17]
	global_load_dwordx4 v[82:85], v145, s[20:21] offset:64
	global_load_dwordx4 v[86:89], v211, s[22:23] offset:64
	global_load_dwordx4 v[90:93], v211, s[38:39] offset:64
	global_load_dwordx4 v[94:97], v211, s[16:17] offset:64
	global_load_dwordx4 v[66:69], v145, s[20:21] offset:512
	global_load_dwordx4 v[70:73], v211, s[22:23] offset:512
	global_load_dwordx4 v[74:77], v211, s[38:39] offset:512
	global_load_dwordx4 v[78:81], v211, s[16:17] offset:512
	global_load_dwordx4 v[50:53], v145, s[20:21] offset:576
	global_load_dwordx4 v[54:57], v211, s[22:23] offset:576
	global_load_dwordx4 v[58:61], v211, s[38:39] offset:576
	global_load_dwordx4 v[62:65], v211, s[16:17] offset:576
	s_waitcnt vmcnt(28)
	v_pk_fma_f32 v[30:31], v[30:31], v[146:147], v[162:163]
	v_pk_fma_f32 v[32:33], v[32:33], v[148:149], v[164:165]
	v_pk_add_f32 v[30:31], v[30:31], v[166:167]
	v_pk_add_f32 v[32:33], v[32:33], v[168:169]
	v_pk_add_f32 v[30:31], v[30:31], v[170:171]
	v_pk_add_f32 v[32:33], v[32:33], v[172:173]
	v_pk_add_f32 v[30:31], v[30:31], v[174:175]
	v_pk_add_f32 v[32:33], v[32:33], v[176:177]
	s_waitcnt vmcnt(24)
	v_pk_fma_f32 v[26:27], v[26:27], v[150:151], v[178:179]
	v_pk_fma_f32 v[28:29], v[28:29], v[152:153], v[180:181]
	v_pk_add_f32 v[26:27], v[26:27], v[182:183]
	v_pk_add_f32 v[28:29], v[28:29], v[184:185]
	v_pk_add_f32 v[26:27], v[26:27], v[186:187]
	v_pk_add_f32 v[28:29], v[28:29], v[188:189]
	v_pk_add_f32 v[26:27], v[26:27], v[190:191]
	v_pk_add_f32 v[28:29], v[28:29], v[192:193]
	s_waitcnt vmcnt(20)
	v_pk_fma_f32 v[22:23], v[22:23], v[154:155], v[194:195]
	v_pk_fma_f32 v[24:25], v[24:25], v[156:157], v[196:197]
	v_pk_add_f32 v[22:23], v[22:23], v[198:199]
	v_pk_add_f32 v[24:25], v[24:25], v[200:201]
	v_pk_add_f32 v[22:23], v[22:23], v[202:203]
	v_pk_add_f32 v[24:25], v[24:25], v[204:205]
	v_pk_add_f32 v[22:23], v[22:23], v[206:207]
	v_pk_add_f32 v[24:25], v[24:25], v[208:209]
	s_waitcnt vmcnt(16)
	v_pk_fma_f32 v[18:19], v[18:19], v[158:159], v[114:115]
	v_pk_fma_f32 v[20:21], v[20:21], v[160:161], v[116:117]
	v_pk_add_f32 v[18:19], v[18:19], v[118:119]
	v_pk_add_f32 v[20:21], v[20:21], v[120:121]
	v_pk_add_f32 v[18:19], v[18:19], v[122:123]
	v_pk_add_f32 v[20:21], v[20:21], v[124:125]
	v_pk_add_f32 v[18:19], v[18:19], v[126:127]
	v_pk_add_f32 v[20:21], v[20:21], v[128:129]
	s_waitcnt vmcnt(12)
	v_pk_fma_f32 v[14:15], v[14:15], v[146:147], v[98:99]
	v_pk_fma_f32 v[16:17], v[16:17], v[148:149], v[100:101]
	v_pk_add_f32 v[14:15], v[14:15], v[102:103]
	v_pk_add_f32 v[16:17], v[16:17], v[104:105]
	v_pk_add_f32 v[14:15], v[14:15], v[106:107]
	v_pk_add_f32 v[16:17], v[16:17], v[108:109]
	v_pk_add_f32 v[14:15], v[14:15], v[110:111]
	v_pk_add_f32 v[16:17], v[16:17], v[112:113]
	s_waitcnt vmcnt(8)
	v_pk_fma_f32 v[10:11], v[10:11], v[150:151], v[82:83]
	v_pk_fma_f32 v[12:13], v[12:13], v[152:153], v[84:85]
	v_pk_add_f32 v[10:11], v[10:11], v[86:87]
	v_pk_add_f32 v[12:13], v[12:13], v[88:89]
	v_pk_add_f32 v[10:11], v[10:11], v[90:91]
	v_pk_add_f32 v[12:13], v[12:13], v[92:93]
	v_pk_add_f32 v[10:11], v[10:11], v[94:95]
	v_pk_add_f32 v[12:13], v[12:13], v[96:97]
	s_waitcnt vmcnt(4)
	v_pk_fma_f32 v[6:7], v[6:7], v[154:155], v[66:67]
	v_pk_fma_f32 v[8:9], v[8:9], v[156:157], v[68:69]
	v_pk_add_f32 v[6:7], v[6:7], v[70:71]
	v_pk_add_f32 v[8:9], v[8:9], v[72:73]
	v_pk_add_f32 v[6:7], v[6:7], v[74:75]
	v_pk_add_f32 v[8:9], v[8:9], v[76:77]
	v_pk_add_f32 v[6:7], v[6:7], v[78:79]
	v_pk_add_f32 v[8:9], v[8:9], v[80:81]
	s_waitcnt vmcnt(0)
	v_pk_fma_f32 v[2:3], v[2:3], v[158:159], v[50:51]
	v_pk_fma_f32 v[4:5], v[4:5], v[160:161], v[52:53]
	v_pk_add_f32 v[2:3], v[2:3], v[54:55]
	v_pk_add_f32 v[4:5], v[4:5], v[56:57]
	v_pk_add_f32 v[2:3], v[2:3], v[58:59]
	v_pk_add_f32 v[4:5], v[4:5], v[60:61]
	v_pk_add_f32 v[2:3], v[2:3], v[62:63]
	v_pk_add_f32 v[4:5], v[4:5], v[64:65]
	global_store_dwordx4 v144, v[30:33], s[20:21]
	global_store_dwordx4 v144, v[26:29], s[20:21] offset:64
	global_store_dwordx4 v144, v[22:25], s[20:21] offset:512
	global_store_dwordx4 v144, v[18:21], s[20:21] offset:576
	global_store_dwordx4 v145, v[14:17], s[20:21]
	global_store_dwordx4 v145, v[10:13], s[20:21] offset:64
	global_store_dwordx4 v145, v[6:9], s[20:21] offset:512
	global_store_dwordx4 v145, v[2:5], s[20:21] offset:576
	s_branch .Lsk_post

; #define PG8_WAIT_V(n) asm volatile("s_waitcnt vmcnt(" #n ")" ::: "memory")
; #define PG8_BAR __builtin_amdgcn_s_barrier()
; template <class Epi, class Sched>
; __device__ __forceinline__ void gemm_phase(LAS unsigned char* lds, const Gemm g, const Sched& S, const Epi& E) {
;     ...
;         E(acc, cur, wr, wc, fr, fq); S.done(cur);
;         if (!has_next) break;
; #pragma unroll
;         for (int a = 0; a < 2; ++a)
; #pragma unroll
;             for (int b = 0; b < 2; ++b)
; #pragma unroll
;                 for (int m = 0; m < 4; ++m)
; #pragma unroll
;                     for (int n = 0; n < 2; ++n) acc[a][b][m][n] = (f32x4){0.f, 0.f, 0.f, 0.f};
;         cur = nxt; cA = nA; cB = nB; ++ui;
;     }
;     PG8_WAIT_V(0);
;     if (wr == 0) PG8_BAR;
;     PG8_BAR;
.Lsk_post:
	s_mov_b64 s[18:19], s[10:11]
	s_mov_b64 s[16:17], s[8:9]
	s_and_b64 vcc, exec, s[0:1]
	s_cbranch_vccz .LBB0_1340
	s_waitcnt vmcnt(0)
	s_cmpk_gt_u32 s24, 0xff
	s_cbranch_scc1 .LBB0_1347
	s_barrier
